# v19: RWKV jobs pinned one per CU, 16-step chunk loop unrolled with 2-step-ahead LDS prefetch, setprio 3 in RWKV job, S5 prefix loop 4-deep load pipelining
# speedup vs baseline: 1.0232x; 1.0232x over previous
.LBB0_448:
	v_ashrrev_i32_e32 v59, 31, v58
	v_lshlrev_b64 v[0:1], 9, v[58:59]
	v_mov_b32_e32 v63, v49
	v_lshl_or_b32 v0, v60, 6, v0
	v_lshl_add_u64 v[0:1], v[0:1], 0, v[62:63]
	v_readlane_b32 s36, v238, 16
	v_lshlrev_b64 v[0:1], 8, v[0:1]
	v_readlane_b32 s38, v238, 18
	v_readlane_b32 s39, v238, 19
	v_lshlrev_b32_e32 v48, 2, v110
	s_xor_b64 s[10:11], exec, -1
	v_lshl_add_u64 v[0:1], s[38:39], 0, v[0:1]
	v_lshl_add_u64 v[0:1], v[0:1], 0, v[48:49]
	v_add_co_u32_e32 v0, vcc, 0x4420000, v0
	v_readlane_b32 s37, v238, 17
	s_nop 0
	v_addc_co_u32_e32 v1, vcc, 0, v1, vcc
	v_readlane_b32 s40, v238, 20
	v_readlane_b32 s41, v238, 21
	v_readlane_b32 s42, v238, 22
	v_readlane_b32 s43, v238, 23
	v_readlane_b32 s44, v238, 24
	v_readlane_b32 s45, v238, 25
	v_readlane_b32 s46, v238, 26
	v_readlane_b32 s47, v238, 27
	v_readlane_b32 s48, v238, 28
	v_readlane_b32 s49, v238, 29
	v_readlane_b32 s50, v238, 30
	v_readlane_b32 s51, v238, 31
	global_store_dwordx4 v[0:1], v[24:27], off
	s_setprio 0
	s_barrier

.LBB0_454:
	s_or_b64 exec, exec, s[8:9]
	s_waitcnt lgkmcnt(0)
	s_barrier
	flat_load_dword v53, v[54:55] sc0 sc1
	s_waitcnt vmcnt(0)
	s_mov_b64 s[10:11], -1
	s_waitcnt lgkmcnt(0)
	v_cmp_gt_i32_e32 vcc, s0, v53
	s_and_saveexec_b64 s[8:9], vcc
	s_cbranch_execz .LBB0_449
	s_setprio 3
	v_bfe_u32 v60, v53, 2, 3
	v_lshlrev_b32_e32 v57, 6, v60
	v_or_b32_e32 v30, v57, v110
	v_readlane_b32 s36, v236, 48
	v_lshlrev_b32_e32 v48, 2, v30
	v_readlane_b32 s37, v236, 49
	v_ashrrev_i32_e32 v58, 5, v53
	v_readlane_b32 s38, v236, 50
	v_lshl_add_u64 v[0:1], s[36:37], 0, v[48:49]
	v_add_co_u32_e32 v0, vcc, 0x1000, v0
	v_readlane_b32 s39, v236, 51
	v_readlane_b32 s40, v236, 52
	v_readlane_b32 s41, v236, 53
	v_readlane_b32 s42, v236, 54
	v_readlane_b32 s43, v236, 55
	v_readlane_b32 s44, v236, 56
	v_readlane_b32 s45, v236, 57
	v_readlane_b32 s46, v236, 58
	v_readlane_b32 s47, v236, 59
	v_readlane_b32 s48, v236, 60
	v_readlane_b32 s49, v236, 61
	v_readlane_b32 s50, v236, 62
	v_readlane_b32 s51, v236, 63
	v_addc_co_u32_e32 v1, vcc, 0, v1, vcc
	v_readlane_b32 s12, v238, 32
	v_lshlrev_b32_e32 v84, 11, v58
	global_load_dwordx4 v[0:3], v[0:1], off
	s_nop 0
	global_load_dwordx4 v[4:7], v48, s[36:37]
	global_load_dwordx4 v[8:11], v48, s[48:49]
	global_load_dwordx4 v[12:15], v48, s[36:37] offset:2048
	global_load_dwordx4 v[16:19], v48, s[50:51]
	v_readlane_b32 s36, v238, 0
	v_readlane_b32 s13, v238, 33
	v_readlane_b32 s37, v238, 1
	v_or_b32_e32 v24, v84, v103
	v_mov_b64_e32 v[26:27], s[12:13]
	v_mad_i64_i32 v[28:29], s[10:11], v24, s1, v[26:27]
	v_ashrrev_i32_e32 v25, 31, v24
	s_nop 0
	global_load_dwordx4 v[20:23], v48, s[36:37]
	v_lshlrev_b32_e32 v48, 1, v30
	v_lshl_add_u64 v[28:29], v[28:29], 0, v[48:49]
	v_readlane_b32 s16, v238, 36
	v_readlane_b32 s17, v238, 37
	v_readlane_b32 s18, v238, 38
	v_readlane_b32 s19, v238, 39
	v_lshl_add_u64 v[30:31], v[50:51], 1, v[28:29]
	global_load_dwordx2 v[46:47], v[28:29], off offset:1024
	global_load_dwordx2 v[42:43], v[28:29], off offset:2048
	global_load_dwordx2 v[40:41], v[28:29], off offset:3072
	global_load_dwordx2 v[82:83], v[30:31], off offset:1024
	global_load_dwordx2 v[80:81], v[30:31], off offset:2048
	global_load_dwordx2 v[62:63], v[30:31], off offset:3072
	v_lshlrev_b64 v[28:29], 10, v[24:25]
	v_lshl_add_u64 v[30:31], s[16:17], 0, v[28:29]
	v_lshl_add_u64 v[28:29], s[18:19], 0, v[28:29]
	v_lshl_add_u64 v[28:29], v[28:29], 0, v[48:49]
	global_load_dwordx2 v[34:35], v[28:29], off
	v_or_b32_e32 v28, v84, v126
	v_mad_i64_i32 v[26:27], s[10:11], v28, s1, v[26:27]
	v_lshl_add_u64 v[30:31], v[30:31], 0, v[48:49]
	v_lshl_add_u64 v[26:27], v[26:27], 0, v[48:49]
	global_load_dwordx2 v[44:45], v[30:31], off
	v_ashrrev_i32_e32 v29, 31, v28
	global_load_dwordx2 v[66:67], v[26:27], off offset:2048
	global_load_dwordx2 v[64:65], v[26:27], off offset:3072
	global_load_dwordx2 v[68:69], v[26:27], off offset:1024
	global_load_dwordx2 v[78:79], v[26:27], off offset:-3584
	global_load_dwordx2 v[76:77], v[26:27], off offset:-2560
	global_load_dwordx2 v[74:75], v[26:27], off offset:-1536
	v_lshlrev_b64 v[26:27], 10, v[28:29]
	v_lshl_add_u64 v[28:29], s[16:17], 0, v[26:27]
	v_lshl_add_u64 v[26:27], s[18:19], 0, v[26:27]
	v_lshl_add_u64 v[28:29], v[28:29], 0, v[48:49]
	v_lshl_add_u64 v[26:27], v[26:27], 0, v[48:49]
	global_load_dwordx2 v[70:71], v[28:29], off
	global_load_dwordx2 v[72:73], v[26:27], off
	v_mov_b32_e32 v32, 0
	v_mov_b32_e32 v33, 0
	v_mov_b32_e32 v30, 0
	v_mov_b32_e32 v31, 0
	v_mov_b32_e32 v38, 0
	v_mov_b32_e32 v39, 0
	v_mov_b32_e32 v36, 0
	v_mov_b32_e32 v37, 0
	v_mov_b32_e32 v26, 0
	v_mov_b32_e32 v27, 0
	v_mov_b32_e32 v28, 0
	v_mov_b32_e32 v29, 0
	v_readlane_b32 s38, v238, 2
	v_readlane_b32 s39, v238, 3
	v_readlane_b32 s40, v238, 4
	v_readlane_b32 s41, v238, 5
	v_readlane_b32 s42, v238, 6
	v_readlane_b32 s43, v238, 7
	v_readlane_b32 s44, v238, 8
	v_readlane_b32 s45, v238, 9
	v_readlane_b32 s46, v238, 10
	v_readlane_b32 s47, v238, 11
	v_readlane_b32 s48, v238, 12
	v_readlane_b32 s49, v238, 13
	v_readlane_b32 s50, v238, 14
	v_readlane_b32 s51, v238, 15
	v_readlane_b32 s14, v238, 34
	v_readlane_b32 s15, v238, 35
	v_readlane_b32 s20, v238, 40
	v_readlane_b32 s21, v238, 41
	v_readlane_b32 s22, v238, 42
	v_readlane_b32 s23, v238, 43
	v_readlane_b32 s24, v238, 44
	v_readlane_b32 s25, v238, 45
	v_readlane_b32 s26, v238, 46
	v_readlane_b32 s27, v238, 47
	s_barrier
	s_and_saveexec_b64 s[10:11], s[4:5]
	s_cbranch_execz .LBB0_457
	s_waitcnt vmcnt(12)
	v_lshlrev_b32_e32 v38, 16, v82
	v_and_b32_e32 v39, 0xffff0000, v82
	v_lshlrev_b32_e32 v36, 16, v83
	v_and_b32_e32 v37, 0xffff0000, v83
	s_waitcnt vmcnt(11)
	v_lshlrev_b32_e32 v32, 16, v80
	v_and_b32_e32 v33, 0xffff0000, v80
	v_lshlrev_b32_e32 v30, 16, v81
	v_and_b32_e32 v31, 0xffff0000, v81
	s_waitcnt vmcnt(10)
	v_lshlrev_b32_e32 v26, 16, v62
	v_and_b32_e32 v27, 0xffff0000, v62
	v_lshlrev_b32_e32 v28, 16, v63
	v_and_b32_e32 v29, 0xffff0000, v63

.LBB0_459:
	v_mov_b64_e32 v[26:27], v[124:125]
	v_mov_b64_e32 v[24:25], v[122:123]
	s_cmpk_gt_u32 s3, 0x7ff
	s_mov_b64 s[10:11], -1
	s_cbranch_scc1 .LBB0_458
	s_mov_b32 s10, 0
	v_mov_b32_e32 v137, v156
	v_mov_b64_e32 v[122:123], v[24:25]
	v_mov_b64_e32 v[124:125], v[26:27]
	ds_read_b128 v[182:185], v127 offset:13056
	ds_read_b128 v[174:177], v127 offset:4352
	ds_read_b128 v[178:181], v127 offset:8704
	ds_read_b128 v[186:189], v127 offset:17408
	ds_read_b32 v190, v53 offset:21760
	ds_read_b128 v[170:173], v127
	ds_read_b128 v[204:207], v127 offset:13312
	ds_read_b128 v[196:199], v127 offset:4608
	ds_read_b128 v[200:203], v127 offset:8960
	ds_read_b128 v[208:211], v127 offset:17664
	ds_read_b32 v212, v53 offset:22016
	ds_read_b128 v[192:195], v127 offset:256
	s_waitcnt lgkmcnt(6)
	v_pk_fma_f32 v[28:29], v[122:123], v[182:183], 0 op_sel_hi:[1,1,0]
	v_pk_fma_f32 v[28:29], v[124:125], v[184:185], v[28:29]
	ds_read_b128 v[226:229], v127 offset:13568
	ds_read_b128 v[218:221], v127 offset:4864
	ds_read_b128 v[222:225], v127 offset:9216
	ds_read_b128 v[230:233], v127 offset:17920
	ds_read_b32 v234, v53 offset:22272
	v_add_f32_e32 v28, v28, v29
	v_pk_mul_f32 v[30:31], v[190:191], v[178:179] op_sel_hi:[0,1]
	v_pk_mul_f32 v[32:33], v[190:191], v[180:181] op_sel_hi:[0,1]
	v_add_f32_dpp v28, v28, v28 quad_perm:[1,0,3,2] row_mask:0xf bank_mask:0xf bound_ctrl:1
	v_pk_fma_f32 v[30:31], v[122:123], v[174:175], v[30:31]
	v_pk_fma_f32 v[32:33], v[124:125], v[176:177], v[32:33]
	v_add_f32_dpp v28, v28, v28 quad_perm:[2,3,0,1] row_mask:0xf bank_mask:0xf bound_ctrl:1
	s_nop 1
	v_add_f32_dpp v28, v28, v28 row_half_mirror row_mask:0xf bank_mask:0xf bound_ctrl:1
	ds_read_b128 v[214:217], v127 offset:512
	s_nop 0
	v_add_f32_dpp v38, v28, v28 row_mirror row_mask:0xf bank_mask:0xf bound_ctrl:1
	v_pk_fma_f32 v[122:123], v[186:187], v[38:39], v[30:31] op_sel_hi:[1,0,1] neg_lo:[1,0,0] neg_hi:[1,0,0]
	v_pk_fma_f32 v[124:125], v[188:189], v[38:39], v[32:33] op_sel_hi:[1,0,1] neg_lo:[1,0,0] neg_hi:[1,0,0]
	s_waitcnt lgkmcnt(6)
	v_pk_fma_f32 v[28:29], v[122:123], v[204:205], 0 op_sel_hi:[1,1,0]
	v_pk_fma_f32 v[28:29], v[124:125], v[206:207], v[28:29]
	ds_read_b128 v[182:185], v127 offset:13824
	ds_read_b128 v[174:177], v127 offset:5120
	ds_read_b128 v[178:181], v127 offset:9472
	ds_read_b128 v[186:189], v127 offset:18176
	ds_read_b32 v190, v53 offset:22528
	v_add_f32_e32 v28, v28, v29
	v_pk_mul_f32 v[30:31], v[212:213], v[200:201] op_sel_hi:[0,1]
	v_pk_mul_f32 v[32:33], v[212:213], v[202:203] op_sel_hi:[0,1]
	v_add_f32_dpp v28, v28, v28 quad_perm:[1,0,3,2] row_mask:0xf bank_mask:0xf bound_ctrl:1
	v_pk_fma_f32 v[30:31], v[122:123], v[196:197], v[30:31]
	v_pk_fma_f32 v[32:33], v[124:125], v[198:199], v[32:33]
	v_add_f32_dpp v28, v28, v28 quad_perm:[2,3,0,1] row_mask:0xf bank_mask:0xf bound_ctrl:1
	v_pk_fma_f32 v[36:37], v[170:171], v[122:123], 0 op_sel_hi:[1,1,0]
	v_pk_fma_f32 v[36:37], v[172:173], v[124:125], v[36:37]
	v_add_f32_dpp v28, v28, v28 row_half_mirror row_mask:0xf bank_mask:0xf bound_ctrl:1
	v_add_f32_e32 v36, v36, v37
	ds_read_b128 v[170:173], v127 offset:768
	v_add_f32_dpp v38, v28, v28 row_mirror row_mask:0xf bank_mask:0xf bound_ctrl:1
	ds_write_b32 v156, v36
	v_pk_fma_f32 v[122:123], v[208:209], v[38:39], v[30:31] op_sel_hi:[1,0,1] neg_lo:[1,0,0] neg_hi:[1,0,0]
	v_pk_fma_f32 v[124:125], v[210:211], v[38:39], v[32:33] op_sel_hi:[1,0,1] neg_lo:[1,0,0] neg_hi:[1,0,0]
	s_waitcnt lgkmcnt(7)
	v_pk_fma_f32 v[28:29], v[122:123], v[226:227], 0 op_sel_hi:[1,1,0]
	v_pk_fma_f32 v[28:29], v[124:125], v[228:229], v[28:29]
	ds_read_b128 v[204:207], v127 offset:14080
	ds_read_b128 v[196:199], v127 offset:5376
	ds_read_b128 v[200:203], v127 offset:9728
	ds_read_b128 v[208:211], v127 offset:18432
	ds_read_b32 v212, v53 offset:22784
	v_add_f32_e32 v28, v28, v29
	v_pk_mul_f32 v[30:31], v[234:235], v[222:223] op_sel_hi:[0,1]
	v_pk_mul_f32 v[32:33], v[234:235], v[224:225] op_sel_hi:[0,1]
	v_add_f32_dpp v28, v28, v28 quad_perm:[1,0,3,2] row_mask:0xf bank_mask:0xf bound_ctrl:1
	v_pk_fma_f32 v[30:31], v[122:123], v[218:219], v[30:31]
	v_pk_fma_f32 v[32:33], v[124:125], v[220:221], v[32:33]
	v_add_f32_dpp v28, v28, v28 quad_perm:[2,3,0,1] row_mask:0xf bank_mask:0xf bound_ctrl:1
	v_pk_fma_f32 v[36:37], v[192:193], v[122:123], 0 op_sel_hi:[1,1,0]
	v_pk_fma_f32 v[36:37], v[194:195], v[124:125], v[36:37]
	v_add_f32_dpp v28, v28, v28 row_half_mirror row_mask:0xf bank_mask:0xf bound_ctrl:1
	v_add_f32_e32 v36, v36, v37
	ds_read_b128 v[192:195], v127 offset:1024
	v_add_f32_dpp v38, v28, v28 row_mirror row_mask:0xf bank_mask:0xf bound_ctrl:1
	ds_write_b32 v156, v36 offset:1024
	v_pk_fma_f32 v[122:123], v[230:231], v[38:39], v[30:31] op_sel_hi:[1,0,1] neg_lo:[1,0,0] neg_hi:[1,0,0]
	v_pk_fma_f32 v[124:125], v[232:233], v[38:39], v[32:33] op_sel_hi:[1,0,1] neg_lo:[1,0,0] neg_hi:[1,0,0]
	s_waitcnt lgkmcnt(8)
	v_pk_fma_f32 v[28:29], v[122:123], v[182:183], 0 op_sel_hi:[1,1,0]
	v_pk_fma_f32 v[28:29], v[124:125], v[184:185], v[28:29]
	ds_read_b128 v[226:229], v127 offset:14336
	ds_read_b128 v[218:221], v127 offset:5632
	ds_read_b128 v[222:225], v127 offset:9984
	ds_read_b128 v[230:233], v127 offset:18688
	ds_read_b32 v234, v53 offset:23040
	v_add_f32_e32 v28, v28, v29
	v_pk_mul_f32 v[30:31], v[190:191], v[178:179] op_sel_hi:[0,1]
	v_pk_mul_f32 v[32:33], v[190:191], v[180:181] op_sel_hi:[0,1]
	v_add_f32_dpp v28, v28, v28 quad_perm:[1,0,3,2] row_mask:0xf bank_mask:0xf bound_ctrl:1
	v_pk_fma_f32 v[30:31], v[122:123], v[174:175], v[30:31]
	v_pk_fma_f32 v[32:33], v[124:125], v[176:177], v[32:33]
	v_add_f32_dpp v28, v28, v28 quad_perm:[2,3,0,1] row_mask:0xf bank_mask:0xf bound_ctrl:1
	v_pk_fma_f32 v[36:37], v[214:215], v[122:123], 0 op_sel_hi:[1,1,0]
	v_pk_fma_f32 v[36:37], v[216:217], v[124:125], v[36:37]
	v_add_f32_dpp v28, v28, v28 row_half_mirror row_mask:0xf bank_mask:0xf bound_ctrl:1
	v_add_f32_e32 v36, v36, v37
	ds_read_b128 v[214:217], v127 offset:1280
	v_add_f32_dpp v38, v28, v28 row_mirror row_mask:0xf bank_mask:0xf bound_ctrl:1
	ds_write_b32 v156, v36 offset:2048
	v_pk_fma_f32 v[122:123], v[186:187], v[38:39], v[30:31] op_sel_hi:[1,0,1] neg_lo:[1,0,0] neg_hi:[1,0,0]
	v_pk_fma_f32 v[124:125], v[188:189], v[38:39], v[32:33] op_sel_hi:[1,0,1] neg_lo:[1,0,0] neg_hi:[1,0,0]
	s_waitcnt lgkmcnt(8)
	v_pk_fma_f32 v[28:29], v[122:123], v[204:205], 0 op_sel_hi:[1,1,0]
	v_pk_fma_f32 v[28:29], v[124:125], v[206:207], v[28:29]
	ds_read_b128 v[182:185], v127 offset:14592
	ds_read_b128 v[174:177], v127 offset:5888
	ds_read_b128 v[178:181], v127 offset:10240
	ds_read_b128 v[186:189], v127 offset:18944
	ds_read_b32 v190, v53 offset:23296
	v_add_f32_e32 v28, v28, v29
	v_pk_mul_f32 v[30:31], v[212:213], v[200:201] op_sel_hi:[0,1]
	v_pk_mul_f32 v[32:33], v[212:213], v[202:203] op_sel_hi:[0,1]
	v_add_f32_dpp v28, v28, v28 quad_perm:[1,0,3,2] row_mask:0xf bank_mask:0xf bound_ctrl:1
	v_pk_fma_f32 v[30:31], v[122:123], v[196:197], v[30:31]
	v_pk_fma_f32 v[32:33], v[124:125], v[198:199], v[32:33]
	v_add_f32_dpp v28, v28, v28 quad_perm:[2,3,0,1] row_mask:0xf bank_mask:0xf bound_ctrl:1
	v_pk_fma_f32 v[36:37], v[170:171], v[122:123], 0 op_sel_hi:[1,1,0]
	v_pk_fma_f32 v[36:37], v[172:173], v[124:125], v[36:37]
	v_add_f32_dpp v28, v28, v28 row_half_mirror row_mask:0xf bank_mask:0xf bound_ctrl:1
	v_add_f32_e32 v36, v36, v37
	ds_read_b128 v[170:173], v127 offset:1536
	v_add_f32_dpp v38, v28, v28 row_mirror row_mask:0xf bank_mask:0xf bound_ctrl:1
	ds_write_b32 v156, v36 offset:3072
	v_pk_fma_f32 v[122:123], v[208:209], v[38:39], v[30:31] op_sel_hi:[1,0,1] neg_lo:[1,0,0] neg_hi:[1,0,0]
	v_pk_fma_f32 v[124:125], v[210:211], v[38:39], v[32:33] op_sel_hi:[1,0,1] neg_lo:[1,0,0] neg_hi:[1,0,0]
	s_waitcnt lgkmcnt(8)
	v_pk_fma_f32 v[28:29], v[122:123], v[226:227], 0 op_sel_hi:[1,1,0]
	v_pk_fma_f32 v[28:29], v[124:125], v[228:229], v[28:29]
	ds_read_b128 v[204:207], v127 offset:14848
	ds_read_b128 v[196:199], v127 offset:6144
	ds_read_b128 v[200:203], v127 offset:10496
	ds_read_b128 v[208:211], v127 offset:19200
	ds_read_b32 v212, v53 offset:23552
	v_add_f32_e32 v28, v28, v29
	v_pk_mul_f32 v[30:31], v[234:235], v[222:223] op_sel_hi:[0,1]
	v_pk_mul_f32 v[32:33], v[234:235], v[224:225] op_sel_hi:[0,1]
	v_add_f32_dpp v28, v28, v28 quad_perm:[1,0,3,2] row_mask:0xf bank_mask:0xf bound_ctrl:1
	v_pk_fma_f32 v[30:31], v[122:123], v[218:219], v[30:31]
	v_pk_fma_f32 v[32:33], v[124:125], v[220:221], v[32:33]
	v_add_f32_dpp v28, v28, v28 quad_perm:[2,3,0,1] row_mask:0xf bank_mask:0xf bound_ctrl:1
	v_pk_fma_f32 v[36:37], v[192:193], v[122:123], 0 op_sel_hi:[1,1,0]
	v_pk_fma_f32 v[36:37], v[194:195], v[124:125], v[36:37]
	v_add_f32_dpp v28, v28, v28 row_half_mirror row_mask:0xf bank_mask:0xf bound_ctrl:1
	v_add_f32_e32 v36, v36, v37
	ds_read_b128 v[192:195], v127 offset:1792
	v_add_f32_dpp v38, v28, v28 row_mirror row_mask:0xf bank_mask:0xf bound_ctrl:1
	ds_write_b32 v156, v36 offset:4096
	v_pk_fma_f32 v[122:123], v[230:231], v[38:39], v[30:31] op_sel_hi:[1,0,1] neg_lo:[1,0,0] neg_hi:[1,0,0]
	v_pk_fma_f32 v[124:125], v[232:233], v[38:39], v[32:33] op_sel_hi:[1,0,1] neg_lo:[1,0,0] neg_hi:[1,0,0]
	s_waitcnt lgkmcnt(8)
	v_pk_fma_f32 v[28:29], v[122:123], v[182:183], 0 op_sel_hi:[1,1,0]
	v_pk_fma_f32 v[28:29], v[124:125], v[184:185], v[28:29]
	ds_read_b128 v[226:229], v127 offset:15104
	ds_read_b128 v[218:221], v127 offset:6400
	ds_read_b128 v[222:225], v127 offset:10752
	ds_read_b128 v[230:233], v127 offset:19456
	ds_read_b32 v234, v53 offset:23808
	v_add_f32_e32 v28, v28, v29
	v_pk_mul_f32 v[30:31], v[190:191], v[178:179] op_sel_hi:[0,1]
	v_pk_mul_f32 v[32:33], v[190:191], v[180:181] op_sel_hi:[0,1]
	v_add_f32_dpp v28, v28, v28 quad_perm:[1,0,3,2] row_mask:0xf bank_mask:0xf bound_ctrl:1
	v_pk_fma_f32 v[30:31], v[122:123], v[174:175], v[30:31]
	v_pk_fma_f32 v[32:33], v[124:125], v[176:177], v[32:33]
	v_add_f32_dpp v28, v28, v28 quad_perm:[2,3,0,1] row_mask:0xf bank_mask:0xf bound_ctrl:1
	v_pk_fma_f32 v[36:37], v[214:215], v[122:123], 0 op_sel_hi:[1,1,0]
	v_pk_fma_f32 v[36:37], v[216:217], v[124:125], v[36:37]
	v_add_f32_dpp v28, v28, v28 row_half_mirror row_mask:0xf bank_mask:0xf bound_ctrl:1
	v_add_f32_e32 v36, v36, v37
	ds_read_b128 v[214:217], v127 offset:2048
	v_add_f32_dpp v38, v28, v28 row_mirror row_mask:0xf bank_mask:0xf bound_ctrl:1
	ds_write_b32 v156, v36 offset:5120
	v_pk_fma_f32 v[122:123], v[186:187], v[38:39], v[30:31] op_sel_hi:[1,0,1] neg_lo:[1,0,0] neg_hi:[1,0,0]
	v_pk_fma_f32 v[124:125], v[188:189], v[38:39], v[32:33] op_sel_hi:[1,0,1] neg_lo:[1,0,0] neg_hi:[1,0,0]
	s_waitcnt lgkmcnt(8)
	v_pk_fma_f32 v[28:29], v[122:123], v[204:205], 0 op_sel_hi:[1,1,0]
	v_pk_fma_f32 v[28:29], v[124:125], v[206:207], v[28:29]
	ds_read_b128 v[182:185], v127 offset:15360
	ds_read_b128 v[174:177], v127 offset:6656
	ds_read_b128 v[178:181], v127 offset:11008
	ds_read_b128 v[186:189], v127 offset:19712
	ds_read_b32 v190, v53 offset:24064
	v_add_f32_e32 v28, v28, v29
	v_pk_mul_f32 v[30:31], v[212:213], v[200:201] op_sel_hi:[0,1]
	v_pk_mul_f32 v[32:33], v[212:213], v[202:203] op_sel_hi:[0,1]
	v_add_f32_dpp v28, v28, v28 quad_perm:[1,0,3,2] row_mask:0xf bank_mask:0xf bound_ctrl:1
	v_pk_fma_f32 v[30:31], v[122:123], v[196:197], v[30:31]
	v_pk_fma_f32 v[32:33], v[124:125], v[198:199], v[32:33]
	v_add_f32_dpp v28, v28, v28 quad_perm:[2,3,0,1] row_mask:0xf bank_mask:0xf bound_ctrl:1
	v_pk_fma_f32 v[36:37], v[170:171], v[122:123], 0 op_sel_hi:[1,1,0]
	v_pk_fma_f32 v[36:37], v[172:173], v[124:125], v[36:37]
	v_add_f32_dpp v28, v28, v28 row_half_mirror row_mask:0xf bank_mask:0xf bound_ctrl:1
	v_add_f32_e32 v36, v36, v37
	ds_read_b128 v[170:173], v127 offset:2304
	v_add_f32_dpp v38, v28, v28 row_mirror row_mask:0xf bank_mask:0xf bound_ctrl:1
	ds_write_b32 v156, v36 offset:6144
	v_pk_fma_f32 v[122:123], v[208:209], v[38:39], v[30:31] op_sel_hi:[1,0,1] neg_lo:[1,0,0] neg_hi:[1,0,0]
	v_pk_fma_f32 v[124:125], v[210:211], v[38:39], v[32:33] op_sel_hi:[1,0,1] neg_lo:[1,0,0] neg_hi:[1,0,0]
	s_waitcnt lgkmcnt(8)
	v_pk_fma_f32 v[28:29], v[122:123], v[226:227], 0 op_sel_hi:[1,1,0]
	v_pk_fma_f32 v[28:29], v[124:125], v[228:229], v[28:29]
	ds_read_b128 v[204:207], v127 offset:15616
	ds_read_b128 v[196:199], v127 offset:6912
	ds_read_b128 v[200:203], v127 offset:11264
	ds_read_b128 v[208:211], v127 offset:19968
	ds_read_b32 v212, v53 offset:24320
	v_add_f32_e32 v28, v28, v29
	v_pk_mul_f32 v[30:31], v[234:235], v[222:223] op_sel_hi:[0,1]
	v_pk_mul_f32 v[32:33], v[234:235], v[224:225] op_sel_hi:[0,1]
	v_add_f32_dpp v28, v28, v28 quad_perm:[1,0,3,2] row_mask:0xf bank_mask:0xf bound_ctrl:1
	v_pk_fma_f32 v[30:31], v[122:123], v[218:219], v[30:31]
	v_pk_fma_f32 v[32:33], v[124:125], v[220:221], v[32:33]
	v_add_f32_dpp v28, v28, v28 quad_perm:[2,3,0,1] row_mask:0xf bank_mask:0xf bound_ctrl:1
	v_pk_fma_f32 v[36:37], v[192:193], v[122:123], 0 op_sel_hi:[1,1,0]
	v_pk_fma_f32 v[36:37], v[194:195], v[124:125], v[36:37]
	v_add_f32_dpp v28, v28, v28 row_half_mirror row_mask:0xf bank_mask:0xf bound_ctrl:1
	v_add_f32_e32 v36, v36, v37
	ds_read_b128 v[192:195], v127 offset:2560
	v_add_f32_dpp v38, v28, v28 row_mirror row_mask:0xf bank_mask:0xf bound_ctrl:1
	ds_write_b32 v156, v36 offset:7168
	v_pk_fma_f32 v[122:123], v[230:231], v[38:39], v[30:31] op_sel_hi:[1,0,1] neg_lo:[1,0,0] neg_hi:[1,0,0]
	v_pk_fma_f32 v[124:125], v[232:233], v[38:39], v[32:33] op_sel_hi:[1,0,1] neg_lo:[1,0,0] neg_hi:[1,0,0]
	s_waitcnt lgkmcnt(8)
	v_pk_fma_f32 v[28:29], v[122:123], v[182:183], 0 op_sel_hi:[1,1,0]
	v_pk_fma_f32 v[28:29], v[124:125], v[184:185], v[28:29]
	ds_read_b128 v[226:229], v127 offset:15872
	ds_read_b128 v[218:221], v127 offset:7168
	ds_read_b128 v[222:225], v127 offset:11520
	ds_read_b128 v[230:233], v127 offset:20224
	ds_read_b32 v234, v53 offset:24576
	v_add_f32_e32 v28, v28, v29
	v_pk_mul_f32 v[30:31], v[190:191], v[178:179] op_sel_hi:[0,1]
	v_pk_mul_f32 v[32:33], v[190:191], v[180:181] op_sel_hi:[0,1]
	v_add_f32_dpp v28, v28, v28 quad_perm:[1,0,3,2] row_mask:0xf bank_mask:0xf bound_ctrl:1
	v_pk_fma_f32 v[30:31], v[122:123], v[174:175], v[30:31]
	v_pk_fma_f32 v[32:33], v[124:125], v[176:177], v[32:33]
	v_add_f32_dpp v28, v28, v28 quad_perm:[2,3,0,1] row_mask:0xf bank_mask:0xf bound_ctrl:1
	v_pk_fma_f32 v[36:37], v[214:215], v[122:123], 0 op_sel_hi:[1,1,0]
	v_pk_fma_f32 v[36:37], v[216:217], v[124:125], v[36:37]
	v_add_f32_dpp v28, v28, v28 row_half_mirror row_mask:0xf bank_mask:0xf bound_ctrl:1
	v_add_f32_e32 v36, v36, v37
	ds_read_b128 v[214:217], v127 offset:2816
	v_add_f32_dpp v38, v28, v28 row_mirror row_mask:0xf bank_mask:0xf bound_ctrl:1
	ds_write_b32 v156, v36 offset:8192
	v_pk_fma_f32 v[122:123], v[186:187], v[38:39], v[30:31] op_sel_hi:[1,0,1] neg_lo:[1,0,0] neg_hi:[1,0,0]
	v_pk_fma_f32 v[124:125], v[188:189], v[38:39], v[32:33] op_sel_hi:[1,0,1] neg_lo:[1,0,0] neg_hi:[1,0,0]
	s_waitcnt lgkmcnt(8)
	v_pk_fma_f32 v[28:29], v[122:123], v[204:205], 0 op_sel_hi:[1,1,0]
	v_pk_fma_f32 v[28:29], v[124:125], v[206:207], v[28:29]
	ds_read_b128 v[182:185], v127 offset:16128
	ds_read_b128 v[174:177], v127 offset:7424
	ds_read_b128 v[178:181], v127 offset:11776
	ds_read_b128 v[186:189], v127 offset:20480
	ds_read_b32 v190, v53 offset:24832
	v_add_f32_e32 v28, v28, v29
	v_pk_mul_f32 v[30:31], v[212:213], v[200:201] op_sel_hi:[0,1]
	v_pk_mul_f32 v[32:33], v[212:213], v[202:203] op_sel_hi:[0,1]
	v_add_f32_dpp v28, v28, v28 quad_perm:[1,0,3,2] row_mask:0xf bank_mask:0xf bound_ctrl:1
	v_pk_fma_f32 v[30:31], v[122:123], v[196:197], v[30:31]
	v_pk_fma_f32 v[32:33], v[124:125], v[198:199], v[32:33]
	v_add_f32_dpp v28, v28, v28 quad_perm:[2,3,0,1] row_mask:0xf bank_mask:0xf bound_ctrl:1
	v_pk_fma_f32 v[36:37], v[170:171], v[122:123], 0 op_sel_hi:[1,1,0]
	v_pk_fma_f32 v[36:37], v[172:173], v[124:125], v[36:37]
	v_add_f32_dpp v28, v28, v28 row_half_mirror row_mask:0xf bank_mask:0xf bound_ctrl:1
	v_add_f32_e32 v36, v36, v37
	ds_read_b128 v[170:173], v127 offset:3072
	v_add_f32_dpp v38, v28, v28 row_mirror row_mask:0xf bank_mask:0xf bound_ctrl:1
	ds_write_b32 v156, v36 offset:9216
	v_pk_fma_f32 v[122:123], v[208:209], v[38:39], v[30:31] op_sel_hi:[1,0,1] neg_lo:[1,0,0] neg_hi:[1,0,0]
	v_pk_fma_f32 v[124:125], v[210:211], v[38:39], v[32:33] op_sel_hi:[1,0,1] neg_lo:[1,0,0] neg_hi:[1,0,0]
	s_waitcnt lgkmcnt(8)
	v_pk_fma_f32 v[28:29], v[122:123], v[226:227], 0 op_sel_hi:[1,1,0]
	v_pk_fma_f32 v[28:29], v[124:125], v[228:229], v[28:29]
	ds_read_b128 v[204:207], v127 offset:16384
	ds_read_b128 v[196:199], v127 offset:7680
	ds_read_b128 v[200:203], v127 offset:12032
	ds_read_b128 v[208:211], v127 offset:20736
	ds_read_b32 v212, v53 offset:25088
	v_add_f32_e32 v28, v28, v29
	v_pk_mul_f32 v[30:31], v[234:235], v[222:223] op_sel_hi:[0,1]
	v_pk_mul_f32 v[32:33], v[234:235], v[224:225] op_sel_hi:[0,1]
	v_add_f32_dpp v28, v28, v28 quad_perm:[1,0,3,2] row_mask:0xf bank_mask:0xf bound_ctrl:1
	v_pk_fma_f32 v[30:31], v[122:123], v[218:219], v[30:31]
	v_pk_fma_f32 v[32:33], v[124:125], v[220:221], v[32:33]
	v_add_f32_dpp v28, v28, v28 quad_perm:[2,3,0,1] row_mask:0xf bank_mask:0xf bound_ctrl:1
	v_pk_fma_f32 v[36:37], v[192:193], v[122:123], 0 op_sel_hi:[1,1,0]
	v_pk_fma_f32 v[36:37], v[194:195], v[124:125], v[36:37]
	v_add_f32_dpp v28, v28, v28 row_half_mirror row_mask:0xf bank_mask:0xf bound_ctrl:1
	v_add_f32_e32 v36, v36, v37
	ds_read_b128 v[192:195], v127 offset:3328
	v_add_f32_dpp v38, v28, v28 row_mirror row_mask:0xf bank_mask:0xf bound_ctrl:1
	ds_write_b32 v156, v36 offset:10240
	v_pk_fma_f32 v[122:123], v[230:231], v[38:39], v[30:31] op_sel_hi:[1,0,1] neg_lo:[1,0,0] neg_hi:[1,0,0]
	v_pk_fma_f32 v[124:125], v[232:233], v[38:39], v[32:33] op_sel_hi:[1,0,1] neg_lo:[1,0,0] neg_hi:[1,0,0]
	s_waitcnt lgkmcnt(8)
	v_pk_fma_f32 v[28:29], v[122:123], v[182:183], 0 op_sel_hi:[1,1,0]
	v_pk_fma_f32 v[28:29], v[124:125], v[184:185], v[28:29]
	ds_read_b128 v[226:229], v127 offset:16640
	ds_read_b128 v[218:221], v127 offset:7936
	ds_read_b128 v[222:225], v127 offset:12288
	ds_read_b128 v[230:233], v127 offset:20992
	ds_read_b32 v234, v53 offset:25344
	v_add_f32_e32 v28, v28, v29
	v_pk_mul_f32 v[30:31], v[190:191], v[178:179] op_sel_hi:[0,1]
	v_pk_mul_f32 v[32:33], v[190:191], v[180:181] op_sel_hi:[0,1]
	v_add_f32_dpp v28, v28, v28 quad_perm:[1,0,3,2] row_mask:0xf bank_mask:0xf bound_ctrl:1
	v_pk_fma_f32 v[30:31], v[122:123], v[174:175], v[30:31]
	v_pk_fma_f32 v[32:33], v[124:125], v[176:177], v[32:33]
	v_add_f32_dpp v28, v28, v28 quad_perm:[2,3,0,1] row_mask:0xf bank_mask:0xf bound_ctrl:1
	v_pk_fma_f32 v[36:37], v[214:215], v[122:123], 0 op_sel_hi:[1,1,0]
	v_pk_fma_f32 v[36:37], v[216:217], v[124:125], v[36:37]
	v_add_f32_dpp v28, v28, v28 row_half_mirror row_mask:0xf bank_mask:0xf bound_ctrl:1
	v_add_f32_e32 v36, v36, v37
	ds_read_b128 v[214:217], v127 offset:3584
	v_add_f32_dpp v38, v28, v28 row_mirror row_mask:0xf bank_mask:0xf bound_ctrl:1
	ds_write_b32 v156, v36 offset:11264
	v_pk_fma_f32 v[122:123], v[186:187], v[38:39], v[30:31] op_sel_hi:[1,0,1] neg_lo:[1,0,0] neg_hi:[1,0,0]
	v_pk_fma_f32 v[124:125], v[188:189], v[38:39], v[32:33] op_sel_hi:[1,0,1] neg_lo:[1,0,0] neg_hi:[1,0,0]
	s_waitcnt lgkmcnt(8)
	v_pk_fma_f32 v[28:29], v[122:123], v[204:205], 0 op_sel_hi:[1,1,0]
	v_pk_fma_f32 v[28:29], v[124:125], v[206:207], v[28:29]
	ds_read_b128 v[182:185], v127 offset:16896
	ds_read_b128 v[174:177], v127 offset:8192
	ds_read_b128 v[178:181], v127 offset:12544
	ds_read_b128 v[186:189], v127 offset:21248
	ds_read_b32 v190, v53 offset:25600
	v_add_f32_e32 v28, v28, v29
	v_pk_mul_f32 v[30:31], v[212:213], v[200:201] op_sel_hi:[0,1]
	v_pk_mul_f32 v[32:33], v[212:213], v[202:203] op_sel_hi:[0,1]
	v_add_f32_dpp v28, v28, v28 quad_perm:[1,0,3,2] row_mask:0xf bank_mask:0xf bound_ctrl:1
	v_pk_fma_f32 v[30:31], v[122:123], v[196:197], v[30:31]
	v_pk_fma_f32 v[32:33], v[124:125], v[198:199], v[32:33]
	v_add_f32_dpp v28, v28, v28 quad_perm:[2,3,0,1] row_mask:0xf bank_mask:0xf bound_ctrl:1
	v_pk_fma_f32 v[36:37], v[170:171], v[122:123], 0 op_sel_hi:[1,1,0]
	v_pk_fma_f32 v[36:37], v[172:173], v[124:125], v[36:37]
	v_add_f32_dpp v28, v28, v28 row_half_mirror row_mask:0xf bank_mask:0xf bound_ctrl:1
	v_add_f32_e32 v36, v36, v37
	ds_read_b128 v[170:173], v127 offset:3840
	v_add_f32_dpp v38, v28, v28 row_mirror row_mask:0xf bank_mask:0xf bound_ctrl:1
	ds_write_b32 v156, v36 offset:12288
	v_pk_fma_f32 v[122:123], v[208:209], v[38:39], v[30:31] op_sel_hi:[1,0,1] neg_lo:[1,0,0] neg_hi:[1,0,0]
	v_pk_fma_f32 v[124:125], v[210:211], v[38:39], v[32:33] op_sel_hi:[1,0,1] neg_lo:[1,0,0] neg_hi:[1,0,0]
	s_waitcnt lgkmcnt(8)
	v_pk_fma_f32 v[28:29], v[122:123], v[226:227], 0 op_sel_hi:[1,1,0]
	v_pk_fma_f32 v[28:29], v[124:125], v[228:229], v[28:29]
	v_add_f32_e32 v28, v28, v29
	v_pk_mul_f32 v[30:31], v[234:235], v[222:223] op_sel_hi:[0,1]
	v_pk_mul_f32 v[32:33], v[234:235], v[224:225] op_sel_hi:[0,1]
	v_add_f32_dpp v28, v28, v28 quad_perm:[1,0,3,2] row_mask:0xf bank_mask:0xf bound_ctrl:1
	v_pk_fma_f32 v[30:31], v[122:123], v[218:219], v[30:31]
	v_pk_fma_f32 v[32:33], v[124:125], v[220:221], v[32:33]
	v_add_f32_dpp v28, v28, v28 quad_perm:[2,3,0,1] row_mask:0xf bank_mask:0xf bound_ctrl:1
	v_pk_fma_f32 v[36:37], v[192:193], v[122:123], 0 op_sel_hi:[1,1,0]
	v_pk_fma_f32 v[36:37], v[194:195], v[124:125], v[36:37]
	v_add_f32_dpp v28, v28, v28 row_half_mirror row_mask:0xf bank_mask:0xf bound_ctrl:1
	v_add_f32_e32 v36, v36, v37
	s_nop 0
	v_add_f32_dpp v38, v28, v28 row_mirror row_mask:0xf bank_mask:0xf bound_ctrl:1
	ds_write_b32 v156, v36 offset:13312
	v_pk_fma_f32 v[122:123], v[230:231], v[38:39], v[30:31] op_sel_hi:[1,0,1] neg_lo:[1,0,0] neg_hi:[1,0,0]
	v_pk_fma_f32 v[124:125], v[232:233], v[38:39], v[32:33] op_sel_hi:[1,0,1] neg_lo:[1,0,0] neg_hi:[1,0,0]
	s_waitcnt lgkmcnt(2)
	v_pk_fma_f32 v[28:29], v[122:123], v[182:183], 0 op_sel_hi:[1,1,0]
	v_pk_fma_f32 v[28:29], v[124:125], v[184:185], v[28:29]
	v_add_f32_e32 v28, v28, v29
	v_pk_mul_f32 v[30:31], v[190:191], v[178:179] op_sel_hi:[0,1]
	v_pk_mul_f32 v[32:33], v[190:191], v[180:181] op_sel_hi:[0,1]
	v_add_f32_dpp v28, v28, v28 quad_perm:[1,0,3,2] row_mask:0xf bank_mask:0xf bound_ctrl:1
	v_pk_fma_f32 v[30:31], v[122:123], v[174:175], v[30:31]
	v_pk_fma_f32 v[32:33], v[124:125], v[176:177], v[32:33]
	v_add_f32_dpp v28, v28, v28 quad_perm:[2,3,0,1] row_mask:0xf bank_mask:0xf bound_ctrl:1
	v_pk_fma_f32 v[36:37], v[214:215], v[122:123], 0 op_sel_hi:[1,1,0]
	v_pk_fma_f32 v[36:37], v[216:217], v[124:125], v[36:37]
	v_add_f32_dpp v28, v28, v28 row_half_mirror row_mask:0xf bank_mask:0xf bound_ctrl:1
	v_add_f32_e32 v36, v36, v37
	s_nop 0
	v_add_f32_dpp v38, v28, v28 row_mirror row_mask:0xf bank_mask:0xf bound_ctrl:1
	ds_write_b32 v156, v36 offset:14336
	v_pk_fma_f32 v[122:123], v[186:187], v[38:39], v[30:31] op_sel_hi:[1,0,1] neg_lo:[1,0,0] neg_hi:[1,0,0]
	v_pk_fma_f32 v[124:125], v[188:189], v[38:39], v[32:33] op_sel_hi:[1,0,1] neg_lo:[1,0,0] neg_hi:[1,0,0]
	v_pk_fma_f32 v[36:37], v[170:171], v[122:123], 0 op_sel_hi:[1,1,0]
	v_pk_fma_f32 v[36:37], v[172:173], v[124:125], v[36:37]
	v_add_f32_e32 v36, v36, v37
	ds_write_b32 v156, v36 offset:15360
	s_waitcnt vmcnt(10) lgkmcnt(6)
	v_lshlrev_b32_e32 v28, 16, v70
	v_and_b32_e32 v29, 0xffff0000, v70
	v_lshlrev_b32_e32 v30, 16, v71
	v_and_b32_e32 v31, 0xffff0000, v71
	v_mul_f32_e32 v28, 0x3fb8aa3b, v28
	v_mul_f32_e32 v29, 0x3fb8aa3b, v29
	v_mul_f32_e32 v30, 0x3fb8aa3b, v30
	v_mul_f32_e32 v31, 0x3fb8aa3b, v31
	s_waitcnt lgkmcnt(5)
	v_lshlrev_b32_e32 v32, 16, v78
	v_and_b32_e32 v33, 0xffff0000, v78
	v_lshlrev_b32_e32 v34, 16, v79
	v_and_b32_e32 v35, 0xffff0000, v79
	s_waitcnt lgkmcnt(1)
	v_lshlrev_b32_e32 v44, 16, v68
	v_and_b32_e32 v45, 0xffff0000, v68
	v_lshlrev_b32_e32 v46, 16, v69
	v_and_b32_e32 v47, 0xffff0000, v69
	v_exp_f32_e32 v28, v28
	v_exp_f32_e32 v29, v29
	v_exp_f32_e32 v30, v30
	v_exp_f32_e32 v31, v31
	v_pk_add_f32 v[32:33], v[32:33], v[44:45] neg_lo:[0,1] neg_hi:[0,1]
	v_pk_add_f32 v[34:35], v[34:35], v[46:47] neg_lo:[0,1] neg_hi:[0,1]
	v_lshlrev_b32_e32 v36, 16, v76
	v_and_b32_e32 v37, 0xffff0000, v76
	v_lshlrev_b32_e32 v68, 16, v66
	v_and_b32_e32 v69, 0xffff0000, v66
	v_pk_fma_f32 v[32:33], v[4:5], v[32:33], v[44:45]
	v_pk_fma_f32 v[34:35], v[6:7], v[34:35], v[46:47]
	s_waitcnt vmcnt(9)
	v_lshlrev_b32_e32 v70, 16, v72
	v_and_b32_e32 v71, 0xffff0000, v72
	ds_write_b128 v154, v[32:35] offset:26112
	ds_write_b128 v154, v[28:31] offset:30464
	v_pk_add_f32 v[28:29], v[36:37], v[68:69] neg_lo:[0,1] neg_hi:[0,1]
	v_lshlrev_b32_e32 v38, 16, v77
	v_pk_fma_f32 v[36:37], v[12:13], v[28:29], v[68:69]
	v_pk_add_f32 v[28:29], v[70:71], -1.0 op_sel_hi:[1,0]
	v_and_b32_e32 v39, 0xffff0000, v77
	v_pk_fma_f32 v[28:29], v[16:17], v[28:29], 1.0 op_sel_hi:[1,1,0]
	v_lshlrev_b32_e32 v66, 16, v67
	v_pk_mul_f32 v[28:29], v[28:29], v[36:37]
	v_and_b32_e32 v67, 0xffff0000, v67
	v_pk_mul_f32 v[30:31], v[32:33], v[28:29]
	v_lshlrev_b32_e32 v72, 16, v73
	v_pk_mul_f32 v[30:31], v[20:21], v[30:31]
	v_and_b32_e32 v73, 0xffff0000, v73
	v_add_f32_e32 v30, 0, v30
	v_add_f32_e32 v44, v31, v30
	v_pk_add_f32 v[30:31], v[38:39], v[66:67] neg_lo:[0,1] neg_hi:[0,1]
	v_lshlrev_b32_e32 v40, 16, v74
	v_pk_fma_f32 v[32:33], v[14:15], v[30:31], v[66:67]
	v_pk_add_f32 v[30:31], v[72:73], -1.0 op_sel_hi:[1,0]
	v_and_b32_e32 v41, 0xffff0000, v74
	v_pk_fma_f32 v[30:31], v[18:19], v[30:31], 1.0 op_sel_hi:[1,1,0]
	v_lshlrev_b32_e32 v42, 16, v75
	v_pk_mul_f32 v[30:31], v[30:31], v[32:33]
	ds_write_b128 v154, v[28:31] offset:34816
	v_pk_mul_f32 v[34:35], v[34:35], v[30:31]
	v_pk_mul_f32 v[28:29], v[8:9], v[36:37]
	v_pk_mul_f32 v[34:35], v[22:23], v[34:35]
	v_pk_mul_f32 v[30:31], v[28:29], v[28:29]
	v_add_f32_e32 v34, v34, v44
	v_add_f32_e32 v34, v35, v34
	v_pk_mul_f32 v[32:33], v[10:11], v[32:33]
	v_add_f32_e32 v30, v30, v31
	v_add_f32_dpp v34, v34, v34 quad_perm:[1,0,3,2] row_mask:0xf bank_mask:0xf bound_ctrl:1
	v_and_b32_e32 v43, 0xffff0000, v75
	v_lshlrev_b32_e32 v74, 16, v64
	v_add_f32_dpp v34, v34, v34 quad_perm:[2,3,0,1] row_mask:0xf bank_mask:0xf bound_ctrl:1
	v_and_b32_e32 v75, 0xffff0000, v64
	v_lshlrev_b32_e32 v64, 16, v65
	v_add_f32_dpp v34, v34, v34 row_half_mirror row_mask:0xf bank_mask:0xf bound_ctrl:1
	v_and_b32_e32 v65, 0xffff0000, v65
	s_or_b32 s10, s3, 16
	v_add_f32_dpp v38, v34, v34 row_mirror row_mask:0xf bank_mask:0xf bound_ctrl:1
	v_pk_mul_f32 v[34:35], v[32:33], v[32:33]
	s_min_u32 s11, s3, 0x7c0
	v_add_f32_e32 v30, v30, v34
	v_add_f32_e32 v30, v35, v30
	v_mov_b32_e32 v137, v156
	s_nop 0
	v_add_f32_dpp v30, v30, v30 quad_perm:[1,0,3,2] row_mask:0xf bank_mask:0xf bound_ctrl:1
	s_nop 1
	v_add_f32_dpp v30, v30, v30 quad_perm:[2,3,0,1] row_mask:0xf bank_mask:0xf bound_ctrl:1
	s_nop 1
	v_add_f32_dpp v30, v30, v30 row_half_mirror row_mask:0xf bank_mask:0xf bound_ctrl:1
	s_nop 1
	v_add_f32_dpp v30, v30, v30 row_mirror row_mask:0xf bank_mask:0xf bound_ctrl:1
	v_max_f32_e32 v30, 0x179abe15, v30
	v_rsq_f32_e32 v30, v30
	s_nop 0
	v_pk_mul_f32 v[28:29], v[28:29], v[30:31] op_sel_hi:[1,0]
	v_pk_mul_f32 v[30:31], v[32:33], v[30:31] op_sel_hi:[1,0]
	ds_write_b128 v154, v[28:31] offset:39168
	v_pk_mul_f32 v[28:29], v[28:29], v[70:71]
	v_pk_mul_f32 v[30:31], v[30:31], v[72:73]
	ds_write_b128 v154, v[28:31] offset:43520
	v_pk_add_f32 v[28:29], v[40:41], v[74:75] neg_lo:[0,1] neg_hi:[0,1]
	v_pk_add_f32 v[30:31], v[42:43], v[64:65] neg_lo:[0,1] neg_hi:[0,1]
	v_pk_fma_f32 v[28:29], v[0:1], v[28:29], v[74:75]
	v_pk_fma_f32 v[30:31], v[2:3], v[30:31], v[64:65]
	ds_write_b128 v154, v[28:31] offset:47872
	v_add_u32_e32 v28, s10, v80
	v_ashrrev_i32_e32 v29, 31, v28
	v_lshlrev_b64 v[28:29], 5, v[28:29]
	v_lshl_add_u64 v[28:29], v[82:83], 0, v[28:29]
	global_store_dword v[28:29], v38, off
	v_add_u32_e32 v28, s11, v59
	v_mad_i64_i32 v[30:31], s[12:13], v28, s1, v[88:89]
	global_load_dwordx2 v[68:69], v[30:31], off offset:1024
	global_load_dwordx2 v[66:67], v[30:31], off offset:2048
	global_load_dwordx2 v[64:65], v[30:31], off offset:3072
	global_load_dwordx2 v[78:79], v[30:31], off offset:-3584
	global_load_dwordx2 v[76:77], v[30:31], off offset:-2560
	global_load_dwordx2 v[74:75], v[30:31], off offset:-1536
	v_ashrrev_i32_e32 v29, 31, v28
	v_lshlrev_b64 v[28:29], 10, v[28:29]
	v_lshl_add_u64 v[30:31], v[84:85], 0, v[28:29]
	v_lshl_add_u64 v[28:29], v[86:87], 0, v[28:29]
	global_load_dwordx2 v[70:71], v[30:31], off
	global_load_dwordx2 v[72:73], v[28:29], off
	ds_read_b128 v[28:31], v135 offset:52224
	ds_read_b128 v[32:35], v135 offset:52240
	ds_read_b128 v[36:39], v135 offset:52256
	ds_read_b128 v[40:43], v135 offset:52272
	s_mov_b32 s11, 0
	s_waitcnt lgkmcnt(3)
	v_mov_b32_e32 v44, v29
	v_mov_b32_e32 v45, v30
	v_mov_b32_e32 v29, v31
	s_waitcnt lgkmcnt(2)
	v_mov_b32_e32 v30, v33
	v_mov_b32_e32 v31, v34
	v_mov_b32_e32 v33, v35
	v_pk_add_f32 v[28:29], v[44:45], v[28:29]
	v_pk_add_f32 v[30:31], v[30:31], v[32:33]
	s_waitcnt lgkmcnt(1)
	v_mov_b32_e32 v32, v37
	v_mov_b32_e32 v34, v39
	v_add_f32_e32 v28, v28, v29
	v_pk_add_f32 v[30:31], v[30:31], v[30:31] op_sel:[0,1] op_sel_hi:[1,0]
	v_pk_add_f32 v[32:33], v[36:37], v[32:33]
	v_pk_add_f32 v[34:35], v[38:39], v[34:35]
	v_add_f32_e32 v28, 0, v28
	s_waitcnt lgkmcnt(0)
	v_mov_b32_e32 v29, v40
	v_mov_b32_e32 v31, v41
	v_mov_b32_e32 v33, v42
	v_mov_b32_e32 v35, v43
	v_pk_add_f32 v[28:29], v[28:29], v[30:31]
	v_pk_add_f32 v[30:31], v[32:33], v[34:35]
	s_nop 0
	v_pk_add_f32 v[28:29], v[28:29], v[30:31]
	s_nop 0
	v_add_f32_e32 v30, v28, v29
	v_or_b32_e32 v28, s3, v63
	v_ashrrev_i32_e32 v29, 31, v28
	v_lshlrev_b64 v[28:29], 12, v[28:29]
	v_lshl_add_u64 v[28:29], v[90:91], 0, v[28:29]
	global_store_dword v[28:29], v30, off offset:2048
	s_barrier
	ds_read_b128 v[182:185], v127 offset:39168
	ds_read_b128 v[174:177], v127 offset:30464
	ds_read_b128 v[178:181], v127 offset:34816
	ds_read_b128 v[186:189], v127 offset:43520
	ds_read_b32 v190, v53 offset:47872
	ds_read_b128 v[170:173], v127 offset:26112
	ds_read_b128 v[204:207], v127 offset:39424
	ds_read_b128 v[196:199], v127 offset:30720
	ds_read_b128 v[200:203], v127 offset:35072
	ds_read_b128 v[208:211], v127 offset:43776
	ds_read_b32 v212, v53 offset:48128
	ds_read_b128 v[192:195], v127 offset:26368
	s_waitcnt lgkmcnt(6)
	v_pk_fma_f32 v[28:29], v[122:123], v[182:183], 0 op_sel_hi:[1,1,0]
	v_pk_fma_f32 v[28:29], v[124:125], v[184:185], v[28:29]
	ds_read_b128 v[226:229], v127 offset:39680
	ds_read_b128 v[218:221], v127 offset:30976
	ds_read_b128 v[222:225], v127 offset:35328
	ds_read_b128 v[230:233], v127 offset:44032
	ds_read_b32 v234, v53 offset:48384
	v_add_f32_e32 v28, v28, v29
	v_pk_mul_f32 v[30:31], v[190:191], v[178:179] op_sel_hi:[0,1]
	v_pk_mul_f32 v[32:33], v[190:191], v[180:181] op_sel_hi:[0,1]
	v_add_f32_dpp v28, v28, v28 quad_perm:[1,0,3,2] row_mask:0xf bank_mask:0xf bound_ctrl:1
	v_pk_fma_f32 v[30:31], v[122:123], v[174:175], v[30:31]
	v_pk_fma_f32 v[32:33], v[124:125], v[176:177], v[32:33]
	v_add_f32_dpp v28, v28, v28 quad_perm:[2,3,0,1] row_mask:0xf bank_mask:0xf bound_ctrl:1
	s_nop 1
	v_add_f32_dpp v28, v28, v28 row_half_mirror row_mask:0xf bank_mask:0xf bound_ctrl:1
	ds_read_b128 v[214:217], v127 offset:26624
	s_nop 0
	v_add_f32_dpp v38, v28, v28 row_mirror row_mask:0xf bank_mask:0xf bound_ctrl:1
	v_pk_fma_f32 v[122:123], v[186:187], v[38:39], v[30:31] op_sel_hi:[1,0,1] neg_lo:[1,0,0] neg_hi:[1,0,0]
	v_pk_fma_f32 v[124:125], v[188:189], v[38:39], v[32:33] op_sel_hi:[1,0,1] neg_lo:[1,0,0] neg_hi:[1,0,0]
	s_waitcnt lgkmcnt(6)
	v_pk_fma_f32 v[28:29], v[122:123], v[204:205], 0 op_sel_hi:[1,1,0]
	v_pk_fma_f32 v[28:29], v[124:125], v[206:207], v[28:29]
	ds_read_b128 v[182:185], v127 offset:39936
	ds_read_b128 v[174:177], v127 offset:31232
	ds_read_b128 v[178:181], v127 offset:35584
	ds_read_b128 v[186:189], v127 offset:44288
	ds_read_b32 v190, v53 offset:48640
	v_add_f32_e32 v28, v28, v29
	v_pk_mul_f32 v[30:31], v[212:213], v[200:201] op_sel_hi:[0,1]
	v_pk_mul_f32 v[32:33], v[212:213], v[202:203] op_sel_hi:[0,1]
	v_add_f32_dpp v28, v28, v28 quad_perm:[1,0,3,2] row_mask:0xf bank_mask:0xf bound_ctrl:1
	v_pk_fma_f32 v[30:31], v[122:123], v[196:197], v[30:31]
	v_pk_fma_f32 v[32:33], v[124:125], v[198:199], v[32:33]
	v_add_f32_dpp v28, v28, v28 quad_perm:[2,3,0,1] row_mask:0xf bank_mask:0xf bound_ctrl:1
	v_pk_fma_f32 v[36:37], v[170:171], v[122:123], 0 op_sel_hi:[1,1,0]
	v_pk_fma_f32 v[36:37], v[172:173], v[124:125], v[36:37]
	v_add_f32_dpp v28, v28, v28 row_half_mirror row_mask:0xf bank_mask:0xf bound_ctrl:1
	v_add_f32_e32 v36, v36, v37
	ds_read_b128 v[170:173], v127 offset:26880
	v_add_f32_dpp v38, v28, v28 row_mirror row_mask:0xf bank_mask:0xf bound_ctrl:1
	ds_write_b32 v156, v36
	v_pk_fma_f32 v[122:123], v[208:209], v[38:39], v[30:31] op_sel_hi:[1,0,1] neg_lo:[1,0,0] neg_hi:[1,0,0]
	v_pk_fma_f32 v[124:125], v[210:211], v[38:39], v[32:33] op_sel_hi:[1,0,1] neg_lo:[1,0,0] neg_hi:[1,0,0]
	s_waitcnt lgkmcnt(7)
	v_pk_fma_f32 v[28:29], v[122:123], v[226:227], 0 op_sel_hi:[1,1,0]
	v_pk_fma_f32 v[28:29], v[124:125], v[228:229], v[28:29]
	ds_read_b128 v[204:207], v127 offset:40192
	ds_read_b128 v[196:199], v127 offset:31488
	ds_read_b128 v[200:203], v127 offset:35840
	ds_read_b128 v[208:211], v127 offset:44544
	ds_read_b32 v212, v53 offset:48896
	v_add_f32_e32 v28, v28, v29
	v_pk_mul_f32 v[30:31], v[234:235], v[222:223] op_sel_hi:[0,1]
	v_pk_mul_f32 v[32:33], v[234:235], v[224:225] op_sel_hi:[0,1]
	v_add_f32_dpp v28, v28, v28 quad_perm:[1,0,3,2] row_mask:0xf bank_mask:0xf bound_ctrl:1
	v_pk_fma_f32 v[30:31], v[122:123], v[218:219], v[30:31]
	v_pk_fma_f32 v[32:33], v[124:125], v[220:221], v[32:33]
	v_add_f32_dpp v28, v28, v28 quad_perm:[2,3,0,1] row_mask:0xf bank_mask:0xf bound_ctrl:1
	v_pk_fma_f32 v[36:37], v[192:193], v[122:123], 0 op_sel_hi:[1,1,0]
	v_pk_fma_f32 v[36:37], v[194:195], v[124:125], v[36:37]
	v_add_f32_dpp v28, v28, v28 row_half_mirror row_mask:0xf bank_mask:0xf bound_ctrl:1
	v_add_f32_e32 v36, v36, v37
	ds_read_b128 v[192:195], v127 offset:27136
	v_add_f32_dpp v38, v28, v28 row_mirror row_mask:0xf bank_mask:0xf bound_ctrl:1
	ds_write_b32 v156, v36 offset:1024
	v_pk_fma_f32 v[122:123], v[230:231], v[38:39], v[30:31] op_sel_hi:[1,0,1] neg_lo:[1,0,0] neg_hi:[1,0,0]
	v_pk_fma_f32 v[124:125], v[232:233], v[38:39], v[32:33] op_sel_hi:[1,0,1] neg_lo:[1,0,0] neg_hi:[1,0,0]
	s_waitcnt lgkmcnt(8)
	v_pk_fma_f32 v[28:29], v[122:123], v[182:183], 0 op_sel_hi:[1,1,0]
	v_pk_fma_f32 v[28:29], v[124:125], v[184:185], v[28:29]
	ds_read_b128 v[226:229], v127 offset:40448
	ds_read_b128 v[218:221], v127 offset:31744
	ds_read_b128 v[222:225], v127 offset:36096
	ds_read_b128 v[230:233], v127 offset:44800
	ds_read_b32 v234, v53 offset:49152
	v_add_f32_e32 v28, v28, v29
	v_pk_mul_f32 v[30:31], v[190:191], v[178:179] op_sel_hi:[0,1]
	v_pk_mul_f32 v[32:33], v[190:191], v[180:181] op_sel_hi:[0,1]
	v_add_f32_dpp v28, v28, v28 quad_perm:[1,0,3,2] row_mask:0xf bank_mask:0xf bound_ctrl:1
	v_pk_fma_f32 v[30:31], v[122:123], v[174:175], v[30:31]
	v_pk_fma_f32 v[32:33], v[124:125], v[176:177], v[32:33]
	v_add_f32_dpp v28, v28, v28 quad_perm:[2,3,0,1] row_mask:0xf bank_mask:0xf bound_ctrl:1
	v_pk_fma_f32 v[36:37], v[214:215], v[122:123], 0 op_sel_hi:[1,1,0]
	v_pk_fma_f32 v[36:37], v[216:217], v[124:125], v[36:37]
	v_add_f32_dpp v28, v28, v28 row_half_mirror row_mask:0xf bank_mask:0xf bound_ctrl:1
	v_add_f32_e32 v36, v36, v37
	ds_read_b128 v[214:217], v127 offset:27392
	v_add_f32_dpp v38, v28, v28 row_mirror row_mask:0xf bank_mask:0xf bound_ctrl:1
	ds_write_b32 v156, v36 offset:2048
	v_pk_fma_f32 v[122:123], v[186:187], v[38:39], v[30:31] op_sel_hi:[1,0,1] neg_lo:[1,0,0] neg_hi:[1,0,0]
	v_pk_fma_f32 v[124:125], v[188:189], v[38:39], v[32:33] op_sel_hi:[1,0,1] neg_lo:[1,0,0] neg_hi:[1,0,0]
	s_waitcnt lgkmcnt(8)
	v_pk_fma_f32 v[28:29], v[122:123], v[204:205], 0 op_sel_hi:[1,1,0]
	v_pk_fma_f32 v[28:29], v[124:125], v[206:207], v[28:29]
	ds_read_b128 v[182:185], v127 offset:40704
	ds_read_b128 v[174:177], v127 offset:32000
	ds_read_b128 v[178:181], v127 offset:36352
	ds_read_b128 v[186:189], v127 offset:45056
	ds_read_b32 v190, v53 offset:49408
	v_add_f32_e32 v28, v28, v29
	v_pk_mul_f32 v[30:31], v[212:213], v[200:201] op_sel_hi:[0,1]
	v_pk_mul_f32 v[32:33], v[212:213], v[202:203] op_sel_hi:[0,1]
	v_add_f32_dpp v28, v28, v28 quad_perm:[1,0,3,2] row_mask:0xf bank_mask:0xf bound_ctrl:1
	v_pk_fma_f32 v[30:31], v[122:123], v[196:197], v[30:31]
	v_pk_fma_f32 v[32:33], v[124:125], v[198:199], v[32:33]
	v_add_f32_dpp v28, v28, v28 quad_perm:[2,3,0,1] row_mask:0xf bank_mask:0xf bound_ctrl:1
	v_pk_fma_f32 v[36:37], v[170:171], v[122:123], 0 op_sel_hi:[1,1,0]
	v_pk_fma_f32 v[36:37], v[172:173], v[124:125], v[36:37]
	v_add_f32_dpp v28, v28, v28 row_half_mirror row_mask:0xf bank_mask:0xf bound_ctrl:1
	v_add_f32_e32 v36, v36, v37
	ds_read_b128 v[170:173], v127 offset:27648
	v_add_f32_dpp v38, v28, v28 row_mirror row_mask:0xf bank_mask:0xf bound_ctrl:1
	ds_write_b32 v156, v36 offset:3072
	v_pk_fma_f32 v[122:123], v[208:209], v[38:39], v[30:31] op_sel_hi:[1,0,1] neg_lo:[1,0,0] neg_hi:[1,0,0]
	v_pk_fma_f32 v[124:125], v[210:211], v[38:39], v[32:33] op_sel_hi:[1,0,1] neg_lo:[1,0,0] neg_hi:[1,0,0]
	s_waitcnt lgkmcnt(8)
	v_pk_fma_f32 v[28:29], v[122:123], v[226:227], 0 op_sel_hi:[1,1,0]
	v_pk_fma_f32 v[28:29], v[124:125], v[228:229], v[28:29]
	ds_read_b128 v[204:207], v127 offset:40960
	ds_read_b128 v[196:199], v127 offset:32256
	ds_read_b128 v[200:203], v127 offset:36608
	ds_read_b128 v[208:211], v127 offset:45312
	ds_read_b32 v212, v53 offset:49664
	v_add_f32_e32 v28, v28, v29
	v_pk_mul_f32 v[30:31], v[234:235], v[222:223] op_sel_hi:[0,1]
	v_pk_mul_f32 v[32:33], v[234:235], v[224:225] op_sel_hi:[0,1]
	v_add_f32_dpp v28, v28, v28 quad_perm:[1,0,3,2] row_mask:0xf bank_mask:0xf bound_ctrl:1
	v_pk_fma_f32 v[30:31], v[122:123], v[218:219], v[30:31]
	v_pk_fma_f32 v[32:33], v[124:125], v[220:221], v[32:33]
	v_add_f32_dpp v28, v28, v28 quad_perm:[2,3,0,1] row_mask:0xf bank_mask:0xf bound_ctrl:1
	v_pk_fma_f32 v[36:37], v[192:193], v[122:123], 0 op_sel_hi:[1,1,0]
	v_pk_fma_f32 v[36:37], v[194:195], v[124:125], v[36:37]
	v_add_f32_dpp v28, v28, v28 row_half_mirror row_mask:0xf bank_mask:0xf bound_ctrl:1
	v_add_f32_e32 v36, v36, v37
	ds_read_b128 v[192:195], v127 offset:27904
	v_add_f32_dpp v38, v28, v28 row_mirror row_mask:0xf bank_mask:0xf bound_ctrl:1
	ds_write_b32 v156, v36 offset:4096
	v_pk_fma_f32 v[122:123], v[230:231], v[38:39], v[30:31] op_sel_hi:[1,0,1] neg_lo:[1,0,0] neg_hi:[1,0,0]
	v_pk_fma_f32 v[124:125], v[232:233], v[38:39], v[32:33] op_sel_hi:[1,0,1] neg_lo:[1,0,0] neg_hi:[1,0,0]
	s_waitcnt lgkmcnt(8)
	v_pk_fma_f32 v[28:29], v[122:123], v[182:183], 0 op_sel_hi:[1,1,0]
	v_pk_fma_f32 v[28:29], v[124:125], v[184:185], v[28:29]
	ds_read_b128 v[226:229], v127 offset:41216
	ds_read_b128 v[218:221], v127 offset:32512
	ds_read_b128 v[222:225], v127 offset:36864
	ds_read_b128 v[230:233], v127 offset:45568
	ds_read_b32 v234, v53 offset:49920
	v_add_f32_e32 v28, v28, v29
	v_pk_mul_f32 v[30:31], v[190:191], v[178:179] op_sel_hi:[0,1]
	v_pk_mul_f32 v[32:33], v[190:191], v[180:181] op_sel_hi:[0,1]
	v_add_f32_dpp v28, v28, v28 quad_perm:[1,0,3,2] row_mask:0xf bank_mask:0xf bound_ctrl:1
	v_pk_fma_f32 v[30:31], v[122:123], v[174:175], v[30:31]
	v_pk_fma_f32 v[32:33], v[124:125], v[176:177], v[32:33]
	v_add_f32_dpp v28, v28, v28 quad_perm:[2,3,0,1] row_mask:0xf bank_mask:0xf bound_ctrl:1
	v_pk_fma_f32 v[36:37], v[214:215], v[122:123], 0 op_sel_hi:[1,1,0]
	v_pk_fma_f32 v[36:37], v[216:217], v[124:125], v[36:37]
	v_add_f32_dpp v28, v28, v28 row_half_mirror row_mask:0xf bank_mask:0xf bound_ctrl:1
	v_add_f32_e32 v36, v36, v37
	ds_read_b128 v[214:217], v127 offset:28160
	v_add_f32_dpp v38, v28, v28 row_mirror row_mask:0xf bank_mask:0xf bound_ctrl:1
	ds_write_b32 v156, v36 offset:5120
	v_pk_fma_f32 v[122:123], v[186:187], v[38:39], v[30:31] op_sel_hi:[1,0,1] neg_lo:[1,0,0] neg_hi:[1,0,0]
	v_pk_fma_f32 v[124:125], v[188:189], v[38:39], v[32:33] op_sel_hi:[1,0,1] neg_lo:[1,0,0] neg_hi:[1,0,0]
	s_waitcnt lgkmcnt(8)
	v_pk_fma_f32 v[28:29], v[122:123], v[204:205], 0 op_sel_hi:[1,1,0]
	v_pk_fma_f32 v[28:29], v[124:125], v[206:207], v[28:29]
	ds_read_b128 v[182:185], v127 offset:41472
	ds_read_b128 v[174:177], v127 offset:32768
	ds_read_b128 v[178:181], v127 offset:37120
	ds_read_b128 v[186:189], v127 offset:45824
	ds_read_b32 v190, v53 offset:50176
	v_add_f32_e32 v28, v28, v29
	v_pk_mul_f32 v[30:31], v[212:213], v[200:201] op_sel_hi:[0,1]
	v_pk_mul_f32 v[32:33], v[212:213], v[202:203] op_sel_hi:[0,1]
	v_add_f32_dpp v28, v28, v28 quad_perm:[1,0,3,2] row_mask:0xf bank_mask:0xf bound_ctrl:1
	v_pk_fma_f32 v[30:31], v[122:123], v[196:197], v[30:31]
	v_pk_fma_f32 v[32:33], v[124:125], v[198:199], v[32:33]
	v_add_f32_dpp v28, v28, v28 quad_perm:[2,3,0,1] row_mask:0xf bank_mask:0xf bound_ctrl:1
	v_pk_fma_f32 v[36:37], v[170:171], v[122:123], 0 op_sel_hi:[1,1,0]
	v_pk_fma_f32 v[36:37], v[172:173], v[124:125], v[36:37]
	v_add_f32_dpp v28, v28, v28 row_half_mirror row_mask:0xf bank_mask:0xf bound_ctrl:1
	v_add_f32_e32 v36, v36, v37
	ds_read_b128 v[170:173], v127 offset:28416
	v_add_f32_dpp v38, v28, v28 row_mirror row_mask:0xf bank_mask:0xf bound_ctrl:1
	ds_write_b32 v156, v36 offset:6144
	v_pk_fma_f32 v[122:123], v[208:209], v[38:39], v[30:31] op_sel_hi:[1,0,1] neg_lo:[1,0,0] neg_hi:[1,0,0]
	v_pk_fma_f32 v[124:125], v[210:211], v[38:39], v[32:33] op_sel_hi:[1,0,1] neg_lo:[1,0,0] neg_hi:[1,0,0]
	s_waitcnt lgkmcnt(8)
	v_pk_fma_f32 v[28:29], v[122:123], v[226:227], 0 op_sel_hi:[1,1,0]
	v_pk_fma_f32 v[28:29], v[124:125], v[228:229], v[28:29]
	ds_read_b128 v[204:207], v127 offset:41728
	ds_read_b128 v[196:199], v127 offset:33024
	ds_read_b128 v[200:203], v127 offset:37376
	ds_read_b128 v[208:211], v127 offset:46080
	ds_read_b32 v212, v53 offset:50432
	v_add_f32_e32 v28, v28, v29
	v_pk_mul_f32 v[30:31], v[234:235], v[222:223] op_sel_hi:[0,1]
	v_pk_mul_f32 v[32:33], v[234:235], v[224:225] op_sel_hi:[0,1]
	v_add_f32_dpp v28, v28, v28 quad_perm:[1,0,3,2] row_mask:0xf bank_mask:0xf bound_ctrl:1
	v_pk_fma_f32 v[30:31], v[122:123], v[218:219], v[30:31]
	v_pk_fma_f32 v[32:33], v[124:125], v[220:221], v[32:33]
	v_add_f32_dpp v28, v28, v28 quad_perm:[2,3,0,1] row_mask:0xf bank_mask:0xf bound_ctrl:1
	v_pk_fma_f32 v[36:37], v[192:193], v[122:123], 0 op_sel_hi:[1,1,0]
	v_pk_fma_f32 v[36:37], v[194:195], v[124:125], v[36:37]
	v_add_f32_dpp v28, v28, v28 row_half_mirror row_mask:0xf bank_mask:0xf bound_ctrl:1
	v_add_f32_e32 v36, v36, v37
	ds_read_b128 v[192:195], v127 offset:28672
	v_add_f32_dpp v38, v28, v28 row_mirror row_mask:0xf bank_mask:0xf bound_ctrl:1
	ds_write_b32 v156, v36 offset:7168
	v_pk_fma_f32 v[122:123], v[230:231], v[38:39], v[30:31] op_sel_hi:[1,0,1] neg_lo:[1,0,0] neg_hi:[1,0,0]
	v_pk_fma_f32 v[124:125], v[232:233], v[38:39], v[32:33] op_sel_hi:[1,0,1] neg_lo:[1,0,0] neg_hi:[1,0,0]
	s_waitcnt lgkmcnt(8)
	v_pk_fma_f32 v[28:29], v[122:123], v[182:183], 0 op_sel_hi:[1,1,0]
	v_pk_fma_f32 v[28:29], v[124:125], v[184:185], v[28:29]
	ds_read_b128 v[226:229], v127 offset:41984
	ds_read_b128 v[218:221], v127 offset:33280
	ds_read_b128 v[222:225], v127 offset:37632
	ds_read_b128 v[230:233], v127 offset:46336
	ds_read_b32 v234, v53 offset:50688
	v_add_f32_e32 v28, v28, v29
	v_pk_mul_f32 v[30:31], v[190:191], v[178:179] op_sel_hi:[0,1]
	v_pk_mul_f32 v[32:33], v[190:191], v[180:181] op_sel_hi:[0,1]
	v_add_f32_dpp v28, v28, v28 quad_perm:[1,0,3,2] row_mask:0xf bank_mask:0xf bound_ctrl:1
	v_pk_fma_f32 v[30:31], v[122:123], v[174:175], v[30:31]
	v_pk_fma_f32 v[32:33], v[124:125], v[176:177], v[32:33]
	v_add_f32_dpp v28, v28, v28 quad_perm:[2,3,0,1] row_mask:0xf bank_mask:0xf bound_ctrl:1
	v_pk_fma_f32 v[36:37], v[214:215], v[122:123], 0 op_sel_hi:[1,1,0]
	v_pk_fma_f32 v[36:37], v[216:217], v[124:125], v[36:37]
	v_add_f32_dpp v28, v28, v28 row_half_mirror row_mask:0xf bank_mask:0xf bound_ctrl:1
	v_add_f32_e32 v36, v36, v37
	ds_read_b128 v[214:217], v127 offset:28928
	v_add_f32_dpp v38, v28, v28 row_mirror row_mask:0xf bank_mask:0xf bound_ctrl:1
	ds_write_b32 v156, v36 offset:8192
	v_pk_fma_f32 v[122:123], v[186:187], v[38:39], v[30:31] op_sel_hi:[1,0,1] neg_lo:[1,0,0] neg_hi:[1,0,0]
	v_pk_fma_f32 v[124:125], v[188:189], v[38:39], v[32:33] op_sel_hi:[1,0,1] neg_lo:[1,0,0] neg_hi:[1,0,0]
	s_waitcnt lgkmcnt(8)
	v_pk_fma_f32 v[28:29], v[122:123], v[204:205], 0 op_sel_hi:[1,1,0]
	v_pk_fma_f32 v[28:29], v[124:125], v[206:207], v[28:29]
	ds_read_b128 v[182:185], v127 offset:42240
	ds_read_b128 v[174:177], v127 offset:33536
	ds_read_b128 v[178:181], v127 offset:37888
	ds_read_b128 v[186:189], v127 offset:46592
	ds_read_b32 v190, v53 offset:50944
	v_add_f32_e32 v28, v28, v29
	v_pk_mul_f32 v[30:31], v[212:213], v[200:201] op_sel_hi:[0,1]
	v_pk_mul_f32 v[32:33], v[212:213], v[202:203] op_sel_hi:[0,1]
	v_add_f32_dpp v28, v28, v28 quad_perm:[1,0,3,2] row_mask:0xf bank_mask:0xf bound_ctrl:1
	v_pk_fma_f32 v[30:31], v[122:123], v[196:197], v[30:31]
	v_pk_fma_f32 v[32:33], v[124:125], v[198:199], v[32:33]
	v_add_f32_dpp v28, v28, v28 quad_perm:[2,3,0,1] row_mask:0xf bank_mask:0xf bound_ctrl:1
	v_pk_fma_f32 v[36:37], v[170:171], v[122:123], 0 op_sel_hi:[1,1,0]
	v_pk_fma_f32 v[36:37], v[172:173], v[124:125], v[36:37]
	v_add_f32_dpp v28, v28, v28 row_half_mirror row_mask:0xf bank_mask:0xf bound_ctrl:1
	v_add_f32_e32 v36, v36, v37
	ds_read_b128 v[170:173], v127 offset:29184
	v_add_f32_dpp v38, v28, v28 row_mirror row_mask:0xf bank_mask:0xf bound_ctrl:1
	ds_write_b32 v156, v36 offset:9216
	v_pk_fma_f32 v[122:123], v[208:209], v[38:39], v[30:31] op_sel_hi:[1,0,1] neg_lo:[1,0,0] neg_hi:[1,0,0]
	v_pk_fma_f32 v[124:125], v[210:211], v[38:39], v[32:33] op_sel_hi:[1,0,1] neg_lo:[1,0,0] neg_hi:[1,0,0]
	s_waitcnt lgkmcnt(8)
	v_pk_fma_f32 v[28:29], v[122:123], v[226:227], 0 op_sel_hi:[1,1,0]
	v_pk_fma_f32 v[28:29], v[124:125], v[228:229], v[28:29]
	ds_read_b128 v[204:207], v127 offset:42496
	ds_read_b128 v[196:199], v127 offset:33792
	ds_read_b128 v[200:203], v127 offset:38144
	ds_read_b128 v[208:211], v127 offset:46848
	ds_read_b32 v212, v53 offset:51200
	v_add_f32_e32 v28, v28, v29
	v_pk_mul_f32 v[30:31], v[234:235], v[222:223] op_sel_hi:[0,1]
	v_pk_mul_f32 v[32:33], v[234:235], v[224:225] op_sel_hi:[0,1]
	v_add_f32_dpp v28, v28, v28 quad_perm:[1,0,3,2] row_mask:0xf bank_mask:0xf bound_ctrl:1
	v_pk_fma_f32 v[30:31], v[122:123], v[218:219], v[30:31]
	v_pk_fma_f32 v[32:33], v[124:125], v[220:221], v[32:33]
	v_add_f32_dpp v28, v28, v28 quad_perm:[2,3,0,1] row_mask:0xf bank_mask:0xf bound_ctrl:1
	v_pk_fma_f32 v[36:37], v[192:193], v[122:123], 0 op_sel_hi:[1,1,0]
	v_pk_fma_f32 v[36:37], v[194:195], v[124:125], v[36:37]
	v_add_f32_dpp v28, v28, v28 row_half_mirror row_mask:0xf bank_mask:0xf bound_ctrl:1
	v_add_f32_e32 v36, v36, v37
	ds_read_b128 v[192:195], v127 offset:29440
	v_add_f32_dpp v38, v28, v28 row_mirror row_mask:0xf bank_mask:0xf bound_ctrl:1
	ds_write_b32 v156, v36 offset:10240
	v_pk_fma_f32 v[122:123], v[230:231], v[38:39], v[30:31] op_sel_hi:[1,0,1] neg_lo:[1,0,0] neg_hi:[1,0,0]
	v_pk_fma_f32 v[124:125], v[232:233], v[38:39], v[32:33] op_sel_hi:[1,0,1] neg_lo:[1,0,0] neg_hi:[1,0,0]
	s_waitcnt lgkmcnt(8)
	v_pk_fma_f32 v[28:29], v[122:123], v[182:183], 0 op_sel_hi:[1,1,0]
	v_pk_fma_f32 v[28:29], v[124:125], v[184:185], v[28:29]
	ds_read_b128 v[226:229], v127 offset:42752
	ds_read_b128 v[218:221], v127 offset:34048
	ds_read_b128 v[222:225], v127 offset:38400
	ds_read_b128 v[230:233], v127 offset:47104
	ds_read_b32 v234, v53 offset:51456
	v_add_f32_e32 v28, v28, v29
	v_pk_mul_f32 v[30:31], v[190:191], v[178:179] op_sel_hi:[0,1]
	v_pk_mul_f32 v[32:33], v[190:191], v[180:181] op_sel_hi:[0,1]
	v_add_f32_dpp v28, v28, v28 quad_perm:[1,0,3,2] row_mask:0xf bank_mask:0xf bound_ctrl:1
	v_pk_fma_f32 v[30:31], v[122:123], v[174:175], v[30:31]
	v_pk_fma_f32 v[32:33], v[124:125], v[176:177], v[32:33]
	v_add_f32_dpp v28, v28, v28 quad_perm:[2,3,0,1] row_mask:0xf bank_mask:0xf bound_ctrl:1
	v_pk_fma_f32 v[36:37], v[214:215], v[122:123], 0 op_sel_hi:[1,1,0]
	v_pk_fma_f32 v[36:37], v[216:217], v[124:125], v[36:37]
	v_add_f32_dpp v28, v28, v28 row_half_mirror row_mask:0xf bank_mask:0xf bound_ctrl:1
	v_add_f32_e32 v36, v36, v37
	ds_read_b128 v[214:217], v127 offset:29696
	v_add_f32_dpp v38, v28, v28 row_mirror row_mask:0xf bank_mask:0xf bound_ctrl:1
	ds_write_b32 v156, v36 offset:11264
	v_pk_fma_f32 v[122:123], v[186:187], v[38:39], v[30:31] op_sel_hi:[1,0,1] neg_lo:[1,0,0] neg_hi:[1,0,0]
	v_pk_fma_f32 v[124:125], v[188:189], v[38:39], v[32:33] op_sel_hi:[1,0,1] neg_lo:[1,0,0] neg_hi:[1,0,0]
	s_waitcnt lgkmcnt(8)
	v_pk_fma_f32 v[28:29], v[122:123], v[204:205], 0 op_sel_hi:[1,1,0]
	v_pk_fma_f32 v[28:29], v[124:125], v[206:207], v[28:29]
	ds_read_b128 v[182:185], v127 offset:43008
	ds_read_b128 v[174:177], v127 offset:34304
	ds_read_b128 v[178:181], v127 offset:38656
	ds_read_b128 v[186:189], v127 offset:47360
	ds_read_b32 v190, v53 offset:51712
	v_add_f32_e32 v28, v28, v29
	v_pk_mul_f32 v[30:31], v[212:213], v[200:201] op_sel_hi:[0,1]
	v_pk_mul_f32 v[32:33], v[212:213], v[202:203] op_sel_hi:[0,1]
	v_add_f32_dpp v28, v28, v28 quad_perm:[1,0,3,2] row_mask:0xf bank_mask:0xf bound_ctrl:1
	v_pk_fma_f32 v[30:31], v[122:123], v[196:197], v[30:31]
	v_pk_fma_f32 v[32:33], v[124:125], v[198:199], v[32:33]
	v_add_f32_dpp v28, v28, v28 quad_perm:[2,3,0,1] row_mask:0xf bank_mask:0xf bound_ctrl:1
	v_pk_fma_f32 v[36:37], v[170:171], v[122:123], 0 op_sel_hi:[1,1,0]
	v_pk_fma_f32 v[36:37], v[172:173], v[124:125], v[36:37]
	v_add_f32_dpp v28, v28, v28 row_half_mirror row_mask:0xf bank_mask:0xf bound_ctrl:1
	v_add_f32_e32 v36, v36, v37
	ds_read_b128 v[170:173], v127 offset:29952
	v_add_f32_dpp v38, v28, v28 row_mirror row_mask:0xf bank_mask:0xf bound_ctrl:1
	ds_write_b32 v156, v36 offset:12288
	v_pk_fma_f32 v[122:123], v[208:209], v[38:39], v[30:31] op_sel_hi:[1,0,1] neg_lo:[1,0,0] neg_hi:[1,0,0]
	v_pk_fma_f32 v[124:125], v[210:211], v[38:39], v[32:33] op_sel_hi:[1,0,1] neg_lo:[1,0,0] neg_hi:[1,0,0]
	s_waitcnt lgkmcnt(8)
	v_pk_fma_f32 v[28:29], v[122:123], v[226:227], 0 op_sel_hi:[1,1,0]
	v_pk_fma_f32 v[28:29], v[124:125], v[228:229], v[28:29]
	v_add_f32_e32 v28, v28, v29
	v_pk_mul_f32 v[30:31], v[234:235], v[222:223] op_sel_hi:[0,1]
	v_pk_mul_f32 v[32:33], v[234:235], v[224:225] op_sel_hi:[0,1]
	v_add_f32_dpp v28, v28, v28 quad_perm:[1,0,3,2] row_mask:0xf bank_mask:0xf bound_ctrl:1
	v_pk_fma_f32 v[30:31], v[122:123], v[218:219], v[30:31]
	v_pk_fma_f32 v[32:33], v[124:125], v[220:221], v[32:33]
	v_add_f32_dpp v28, v28, v28 quad_perm:[2,3,0,1] row_mask:0xf bank_mask:0xf bound_ctrl:1
	v_pk_fma_f32 v[36:37], v[192:193], v[122:123], 0 op_sel_hi:[1,1,0]
	v_pk_fma_f32 v[36:37], v[194:195], v[124:125], v[36:37]
	v_add_f32_dpp v28, v28, v28 row_half_mirror row_mask:0xf bank_mask:0xf bound_ctrl:1
	v_add_f32_e32 v36, v36, v37
	s_nop 0
	v_add_f32_dpp v38, v28, v28 row_mirror row_mask:0xf bank_mask:0xf bound_ctrl:1
	ds_write_b32 v156, v36 offset:13312
	v_pk_fma_f32 v[122:123], v[230:231], v[38:39], v[30:31] op_sel_hi:[1,0,1] neg_lo:[1,0,0] neg_hi:[1,0,0]
	v_pk_fma_f32 v[124:125], v[232:233], v[38:39], v[32:33] op_sel_hi:[1,0,1] neg_lo:[1,0,0] neg_hi:[1,0,0]
	s_waitcnt lgkmcnt(2)
	v_pk_fma_f32 v[28:29], v[122:123], v[182:183], 0 op_sel_hi:[1,1,0]
	v_pk_fma_f32 v[28:29], v[124:125], v[184:185], v[28:29]
	v_add_f32_e32 v28, v28, v29
	v_pk_mul_f32 v[30:31], v[190:191], v[178:179] op_sel_hi:[0,1]
	v_pk_mul_f32 v[32:33], v[190:191], v[180:181] op_sel_hi:[0,1]
	v_add_f32_dpp v28, v28, v28 quad_perm:[1,0,3,2] row_mask:0xf bank_mask:0xf bound_ctrl:1
	v_pk_fma_f32 v[30:31], v[122:123], v[174:175], v[30:31]
	v_pk_fma_f32 v[32:33], v[124:125], v[176:177], v[32:33]
	v_add_f32_dpp v28, v28, v28 quad_perm:[2,3,0,1] row_mask:0xf bank_mask:0xf bound_ctrl:1
	v_pk_fma_f32 v[36:37], v[214:215], v[122:123], 0 op_sel_hi:[1,1,0]
	v_pk_fma_f32 v[36:37], v[216:217], v[124:125], v[36:37]
	v_add_f32_dpp v28, v28, v28 row_half_mirror row_mask:0xf bank_mask:0xf bound_ctrl:1
	v_add_f32_e32 v36, v36, v37
	s_nop 0
	v_add_f32_dpp v38, v28, v28 row_mirror row_mask:0xf bank_mask:0xf bound_ctrl:1
	ds_write_b32 v156, v36 offset:14336
	v_pk_fma_f32 v[122:123], v[186:187], v[38:39], v[30:31] op_sel_hi:[1,0,1] neg_lo:[1,0,0] neg_hi:[1,0,0]
	v_pk_fma_f32 v[124:125], v[188:189], v[38:39], v[32:33] op_sel_hi:[1,0,1] neg_lo:[1,0,0] neg_hi:[1,0,0]
	v_pk_fma_f32 v[36:37], v[170:171], v[122:123], 0 op_sel_hi:[1,1,0]
	v_pk_fma_f32 v[36:37], v[172:173], v[124:125], v[36:37]
	v_add_f32_e32 v36, v36, v37
	ds_write_b32 v156, v36 offset:15360
	s_waitcnt vmcnt(11) lgkmcnt(3)
	v_lshlrev_b32_e32 v28, 16, v112
	v_and_b32_e32 v29, 0xffff0000, v112
	v_lshlrev_b32_e32 v30, 16, v113
	v_and_b32_e32 v31, 0xffff0000, v113
	v_mul_f32_e32 v28, 0x3fb8aa3b, v28
	v_mul_f32_e32 v29, 0x3fb8aa3b, v29
	v_mul_f32_e32 v30, 0x3fb8aa3b, v30
	v_mul_f32_e32 v31, 0x3fb8aa3b, v31
	s_waitcnt lgkmcnt(2)
	v_lshlrev_b32_e32 v32, 16, v120
	v_and_b32_e32 v33, 0xffff0000, v120
	v_lshlrev_b32_e32 v34, 16, v121
	v_and_b32_e32 v35, 0xffff0000, v121
	s_waitcnt lgkmcnt(1)
	v_lshlrev_b32_e32 v44, 16, v108
	v_and_b32_e32 v45, 0xffff0000, v108
	v_lshlrev_b32_e32 v46, 16, v109
	v_and_b32_e32 v47, 0xffff0000, v109
	v_exp_f32_e32 v28, v28
	v_exp_f32_e32 v29, v29
	v_exp_f32_e32 v30, v30
	v_exp_f32_e32 v31, v31
	v_pk_add_f32 v[32:33], v[32:33], v[44:45] neg_lo:[0,1] neg_hi:[0,1]
	v_pk_add_f32 v[34:35], v[34:35], v[46:47] neg_lo:[0,1] neg_hi:[0,1]
	v_lshlrev_b32_e32 v36, 16, v118
	v_and_b32_e32 v37, 0xffff0000, v118
	v_lshlrev_b32_e32 v108, 16, v94
	v_and_b32_e32 v109, 0xffff0000, v94
	v_pk_fma_f32 v[32:33], v[4:5], v[32:33], v[44:45]
	v_pk_fma_f32 v[34:35], v[6:7], v[34:35], v[46:47]
	s_waitcnt vmcnt(10)
	v_lshlrev_b32_e32 v112, 16, v114
	v_and_b32_e32 v113, 0xffff0000, v114
	ds_write_b128 v154, v[32:35]
	ds_write_b128 v154, v[28:31] offset:4352
	v_pk_add_f32 v[28:29], v[36:37], v[108:109] neg_lo:[0,1] neg_hi:[0,1]
	v_lshlrev_b32_e32 v38, 16, v119
	v_pk_fma_f32 v[36:37], v[12:13], v[28:29], v[108:109]
	v_pk_add_f32 v[28:29], v[112:113], -1.0 op_sel_hi:[1,0]
	v_and_b32_e32 v39, 0xffff0000, v119
	v_pk_fma_f32 v[28:29], v[16:17], v[28:29], 1.0 op_sel_hi:[1,1,0]
	v_lshlrev_b32_e32 v94, 16, v95
	v_pk_mul_f32 v[28:29], v[28:29], v[36:37]
	v_and_b32_e32 v95, 0xffff0000, v95
	v_pk_mul_f32 v[30:31], v[32:33], v[28:29]
	v_lshlrev_b32_e32 v114, 16, v115
	v_pk_mul_f32 v[30:31], v[20:21], v[30:31]
	v_and_b32_e32 v115, 0xffff0000, v115
	v_add_f32_e32 v30, 0, v30
	v_add_f32_e32 v44, v31, v30
	v_pk_add_f32 v[30:31], v[38:39], v[94:95] neg_lo:[0,1] neg_hi:[0,1]
	v_lshlrev_b32_e32 v40, 16, v116
	v_pk_fma_f32 v[32:33], v[14:15], v[30:31], v[94:95]
	v_pk_add_f32 v[30:31], v[114:115], -1.0 op_sel_hi:[1,0]
	v_and_b32_e32 v41, 0xffff0000, v116
	v_pk_fma_f32 v[30:31], v[18:19], v[30:31], 1.0 op_sel_hi:[1,1,0]
	v_lshlrev_b32_e32 v42, 16, v117
	v_pk_mul_f32 v[30:31], v[30:31], v[32:33]
	ds_write_b128 v154, v[28:31] offset:8704
	v_pk_mul_f32 v[34:35], v[34:35], v[30:31]
	v_pk_mul_f32 v[28:29], v[8:9], v[36:37]
	v_pk_mul_f32 v[34:35], v[22:23], v[34:35]
	v_pk_mul_f32 v[30:31], v[28:29], v[28:29]
	v_add_f32_e32 v34, v34, v44
	v_add_f32_e32 v34, v35, v34
	v_pk_mul_f32 v[32:33], v[10:11], v[32:33]
	v_add_f32_e32 v30, v30, v31
	v_add_f32_dpp v34, v34, v34 quad_perm:[1,0,3,2] row_mask:0xf bank_mask:0xf bound_ctrl:1
	v_and_b32_e32 v43, 0xffff0000, v117
	v_lshlrev_b32_e32 v116, 16, v92
	v_add_f32_dpp v34, v34, v34 quad_perm:[2,3,0,1] row_mask:0xf bank_mask:0xf bound_ctrl:1
	v_and_b32_e32 v117, 0xffff0000, v92
	v_lshlrev_b32_e32 v92, 16, v93
	v_add_f32_dpp v34, v34, v34 row_half_mirror row_mask:0xf bank_mask:0xf bound_ctrl:1
	v_and_b32_e32 v93, 0xffff0000, v93
	s_add_i32 s12, s3, 32
	v_add_f32_dpp v38, v34, v34 row_mirror row_mask:0xf bank_mask:0xf bound_ctrl:1
	v_pk_mul_f32 v[34:35], v[32:33], v[32:33]
	s_min_u32 s11, s12, 0x7f0
	v_add_f32_e32 v30, v30, v34
	v_add_f32_e32 v30, v35, v30
	s_min_u32 s3, s3, 0x7b0
	s_nop 0
	v_add_f32_dpp v30, v30, v30 quad_perm:[1,0,3,2] row_mask:0xf bank_mask:0xf bound_ctrl:1
	s_nop 1
	v_add_f32_dpp v30, v30, v30 quad_perm:[2,3,0,1] row_mask:0xf bank_mask:0xf bound_ctrl:1
	s_nop 1
	v_add_f32_dpp v30, v30, v30 row_half_mirror row_mask:0xf bank_mask:0xf bound_ctrl:1
	s_nop 1
	v_add_f32_dpp v30, v30, v30 row_mirror row_mask:0xf bank_mask:0xf bound_ctrl:1
	v_max_f32_e32 v30, 0x179abe15, v30
	v_rsq_f32_e32 v30, v30
	s_nop 0
	v_pk_mul_f32 v[28:29], v[28:29], v[30:31] op_sel_hi:[1,0]
	v_pk_mul_f32 v[30:31], v[32:33], v[30:31] op_sel_hi:[1,0]
	ds_write_b128 v154, v[28:31] offset:13056
	v_pk_mul_f32 v[28:29], v[28:29], v[112:113]
	v_pk_mul_f32 v[30:31], v[30:31], v[114:115]
	ds_write_b128 v154, v[28:31] offset:17408
	v_pk_add_f32 v[28:29], v[40:41], v[116:117] neg_lo:[0,1] neg_hi:[0,1]
	v_pk_add_f32 v[30:31], v[42:43], v[92:93] neg_lo:[0,1] neg_hi:[0,1]
	v_pk_fma_f32 v[28:29], v[0:1], v[28:29], v[116:117]
	v_pk_fma_f32 v[30:31], v[2:3], v[30:31], v[92:93]
	ds_write_b128 v154, v[28:31] offset:21760
	v_add_u32_e32 v28, s11, v80
	v_ashrrev_i32_e32 v29, 31, v28
	v_lshlrev_b64 v[28:29], 5, v[28:29]
	v_lshl_add_u64 v[28:29], v[82:83], 0, v[28:29]
	global_store_dword v[28:29], v38, off
	v_add_u32_e32 v28, s3, v81
	v_mad_i64_i32 v[30:31], s[14:15], v28, s1, v[88:89]
	global_load_dwordx2 v[108:109], v[30:31], off offset:1024
	global_load_dwordx2 v[94:95], v[30:31], off offset:2048
	global_load_dwordx2 v[92:93], v[30:31], off offset:3072
	global_load_dwordx2 v[120:121], v[30:31], off offset:-3584
	global_load_dwordx2 v[118:119], v[30:31], off offset:-2560
	global_load_dwordx2 v[116:117], v[30:31], off offset:-1536
	v_ashrrev_i32_e32 v29, 31, v28
	v_lshlrev_b64 v[28:29], 10, v[28:29]
	v_lshl_add_u64 v[30:31], v[84:85], 0, v[28:29]
	v_lshl_add_u64 v[28:29], v[86:87], 0, v[28:29]
	global_load_dwordx2 v[112:113], v[30:31], off
	global_load_dwordx2 v[114:115], v[28:29], off
	ds_read_b128 v[28:31], v135 offset:52224
	ds_read_b128 v[32:35], v135 offset:52240
	ds_read_b128 v[36:39], v135 offset:52256
	ds_read_b128 v[40:43], v135 offset:52272
	s_mov_b32 s3, s12
	s_waitcnt lgkmcnt(3)
	v_mov_b32_e32 v44, v29
	v_mov_b32_e32 v45, v30
	v_mov_b32_e32 v29, v31
	s_waitcnt lgkmcnt(2)
	v_mov_b32_e32 v30, v33
	v_mov_b32_e32 v31, v34
	v_mov_b32_e32 v33, v35
	v_pk_add_f32 v[28:29], v[44:45], v[28:29]
	v_pk_add_f32 v[30:31], v[30:31], v[32:33]
	s_waitcnt lgkmcnt(1)
	v_mov_b32_e32 v32, v37
	v_mov_b32_e32 v34, v39
	v_add_f32_e32 v28, v28, v29
	v_pk_add_f32 v[30:31], v[30:31], v[30:31] op_sel:[0,1] op_sel_hi:[1,0]
	v_pk_add_f32 v[32:33], v[36:37], v[32:33]
	v_pk_add_f32 v[34:35], v[38:39], v[34:35]
	v_add_f32_e32 v28, 0, v28
	s_waitcnt lgkmcnt(0)
	v_mov_b32_e32 v29, v40
	v_mov_b32_e32 v31, v41
	v_mov_b32_e32 v33, v42
	v_mov_b32_e32 v35, v43
	v_pk_add_f32 v[28:29], v[28:29], v[30:31]
	v_pk_add_f32 v[30:31], v[32:33], v[34:35]
	s_nop 0
	v_pk_add_f32 v[28:29], v[28:29], v[30:31]
	s_nop 0
	v_add_f32_e32 v30, v28, v29
	v_or_b32_e32 v28, s10, v63
	v_ashrrev_i32_e32 v29, 31, v28
	v_lshlrev_b64 v[28:29], 12, v[28:29]
	v_lshl_add_u64 v[28:29], v[90:91], 0, v[28:29]
	s_mov_b64 s[10:11], 0
	global_store_dword v[28:29], v30, off offset:2048
	s_barrier
	s_branch .LBB0_458

.LBB0_512:
	v_lshl_add_u32 v8, v0, 2, v99
	v_bfe_u32 v6, v8, 5, 5
	v_lshlrev_b32_e32 v74, 6, v6
	v_or_b32_e32 v0, v74, v101
	v_and_b32_e32 v75, 31, v8
	v_mov_b32_e32 v69, 0
	v_cmp_ne_u32_e32 vcc, 0, v75
	v_lshlrev_b32_e32 v7, 2, v0
	v_mov_b32_e32 v68, v69
	v_mov_b32_e32 v70, v69
	v_mov_b32_e32 v71, v69
	s_and_saveexec_b64 s[74:75], vcc
	s_cbranch_execz .LBB0_516
	global_load_dword v0, v7, s[88:89]
	global_load_dword v2, v7, s[90:91]
	global_load_dword v1, v7, s[88:89] offset:128
	global_load_dword v3, v7, s[90:91] offset:128
	v_and_b32_e32 v4, 0xffffffe0, v8
	v_ashrrev_i32_e32 v5, 31, v4
	v_lshlrev_b64 v[4:5], 9, v[4:5]
	v_mov_b32_e32 v68, 0
	v_lshl_add_u64 v[4:5], v[136:137], 0, v[4:5]
	s_mov_b64 s[76:77], 0
	v_mov_b32_e32 v9, v75
	v_mov_b32_e32 v69, v68
	v_mov_b32_e32 v70, v68
	v_mov_b32_e32 v71, v68
	v_readfirstlane_b32 s98, v75
	global_load_dword v240, v[4:5], off offset:-256
	global_load_dword v241, v[4:5], off offset:-128
	global_load_dword v242, v[4:5], off offset:0
	global_load_dword v243, v[4:5], off offset:128
	global_load_dword v244, v[4:5], off offset:256
	global_load_dword v245, v[4:5], off offset:384
	global_load_dword v246, v[4:5], off offset:512
	global_load_dword v247, v[4:5], off offset:640
	global_load_dword v248, v[4:5], off offset:768
	global_load_dword v249, v[4:5], off offset:896
	global_load_dword v250, v[4:5], off offset:1024
	global_load_dword v251, v[4:5], off offset:1152
	global_load_dword v252, v[4:5], off offset:1280
	global_load_dword v253, v[4:5], off offset:1408
	global_load_dword v254, v[4:5], off offset:1536
	global_load_dword v255, v[4:5], off offset:1664
.Lmy_s5p_loop:
	s_waitcnt vmcnt(12)
	v_pk_mul_f32 v[14:15], v[2:3], v[68:69]
	v_pk_mul_f32 v[16:17], v[2:3], v[70:71]
	v_pk_fma_f32 v[14:15], v[0:1], v[70:71], v[14:15] neg_lo:[0,0,1] neg_hi:[0,0,1]
	v_pk_fma_f32 v[16:17], v[0:1], v[68:69], v[16:17]
	v_pk_add_f32 v[70:71], v[240:241], v[14:15]
	v_pk_add_f32 v[68:69], v[16:17], v[242:243]
	global_load_dword v240, v[4:5], off offset:1792
	global_load_dword v241, v[4:5], off offset:1920
	global_load_dword v242, v[4:5], off offset:2048
	global_load_dword v243, v[4:5], off offset:2176
	s_sub_u32 s98, s98, 1
	s_cmp_eq_u32 s98, 0
	s_cbranch_scc1 .Lmy_s5p_done
	s_waitcnt vmcnt(12)
	v_pk_mul_f32 v[14:15], v[2:3], v[68:69]
	v_pk_mul_f32 v[16:17], v[2:3], v[70:71]
	v_pk_fma_f32 v[14:15], v[0:1], v[70:71], v[14:15] neg_lo:[0,0,1] neg_hi:[0,0,1]
	v_pk_fma_f32 v[16:17], v[0:1], v[68:69], v[16:17]
	v_pk_add_f32 v[70:71], v[244:245], v[14:15]
	v_pk_add_f32 v[68:69], v[16:17], v[246:247]
	global_load_dword v244, v[4:5], off offset:2304
	global_load_dword v245, v[4:5], off offset:2432
	global_load_dword v246, v[4:5], off offset:2560
	global_load_dword v247, v[4:5], off offset:2688
	s_sub_u32 s98, s98, 1
	s_cmp_eq_u32 s98, 0
	s_cbranch_scc1 .Lmy_s5p_done
	s_waitcnt vmcnt(12)
	v_pk_mul_f32 v[14:15], v[2:3], v[68:69]
	v_pk_mul_f32 v[16:17], v[2:3], v[70:71]
	v_pk_fma_f32 v[14:15], v[0:1], v[70:71], v[14:15] neg_lo:[0,0,1] neg_hi:[0,0,1]
	v_pk_fma_f32 v[16:17], v[0:1], v[68:69], v[16:17]
	v_pk_add_f32 v[70:71], v[248:249], v[14:15]
	v_pk_add_f32 v[68:69], v[16:17], v[250:251]
	global_load_dword v248, v[4:5], off offset:2816
	global_load_dword v249, v[4:5], off offset:2944
	global_load_dword v250, v[4:5], off offset:3072
	global_load_dword v251, v[4:5], off offset:3200
	s_sub_u32 s98, s98, 1
	s_cmp_eq_u32 s98, 0
	s_cbranch_scc1 .Lmy_s5p_done
	s_waitcnt vmcnt(12)
	v_pk_mul_f32 v[14:15], v[2:3], v[68:69]
	v_pk_mul_f32 v[16:17], v[2:3], v[70:71]
	v_pk_fma_f32 v[14:15], v[0:1], v[70:71], v[14:15] neg_lo:[0,0,1] neg_hi:[0,0,1]
	v_pk_fma_f32 v[16:17], v[0:1], v[68:69], v[16:17]
	v_pk_add_f32 v[70:71], v[252:253], v[14:15]
	v_pk_add_f32 v[68:69], v[16:17], v[254:255]
	global_load_dword v252, v[4:5], off offset:3328
	global_load_dword v253, v[4:5], off offset:3456
	global_load_dword v254, v[4:5], off offset:3584
	global_load_dword v255, v[4:5], off offset:3712
	s_sub_u32 s98, s98, 1
	s_cmp_eq_u32 s98, 0
	s_cbranch_scc1 .Lmy_s5p_done
	s_mov_b64 s[14:15], 0x800
	v_lshl_add_u64 v[4:5], v[4:5], 0, s[14:15]
	s_branch .Lmy_s5p_loop
.Lmy_s5p_done:
	s_or_b64 exec, exec, s[76:77]
.LBB0_516:
	s_or_b64 exec, exec, s[74:75]
	v_lshlrev_b32_e32 v0, 1, v8
	v_lshlrev_b32_e32 v2, 11, v6
	v_and_b32_e32 v76, 0xfffff800, v0
	v_or_b32_e32 v0, v2, v98
	v_readlane_b32 s16, v238, 32
	v_lshl_or_b32 v72, v75, 6, v76
	v_lshlrev_b32_e32 v112, 1, v0
	v_or_b32_e32 v2, v2, v161
	v_readlane_b32 s17, v238, 33
	global_load_dword v90, v7, s[84:85]
	global_load_dword v89, v7, s[86:87]
	global_load_dword v83, v7, s[84:85] offset:128
	global_load_dword v82, v7, s[86:87] offset:128
	v_lshl_add_u64 v[0:1], v[120:121], 0, v[112:113]
	v_lshlrev_b32_e32 v112, 1, v2
	v_or_b32_e32 v95, v72, v101
	v_mov_b64_e32 v[4:5], s[16:17]
	v_lshl_add_u64 v[2:3], v[122:123], 0, v[112:113]
	v_mad_i64_i32 v[4:5], s[14:15], v95, s82, v[4:5]
	v_lshlrev_b32_e32 v112, 5, v6
	v_lshl_add_u64 v[4:5], v[4:5], 0, v[112:113]
	v_mov_b32_e32 v109, v113
	v_lshl_add_u64 v[4:5], v[4:5], 0, v[108:109]
	global_load_dwordx4 v[64:67], v[4:5], off
	global_load_dwordx4 v[60:63], v[0:1], off
	global_load_dwordx4 v[56:59], v[0:1], off offset:2048
	v_lshlrev_b32_e32 v109, 4, v6
	v_cmp_lt_i32_e32 vcc, v152, v117
	v_or_b32_e32 v5, v109, v155
	v_readlane_b32 s36, v236, 32
	v_cndmask_b32_e32 v4, v103, v152, vcc
	v_lshlrev_b32_e32 v88, 2, v4
	v_lshlrev_b32_e32 v4, 2, v5
	v_readlane_b32 s46, v236, 42
	v_readlane_b32 s47, v236, 43
	s_nop 4
	global_load_dword v81, v4, s[46:47]
	global_load_dwordx4 v[52:55], v[0:1], off offset:1024
	global_load_dwordx4 v[48:51], v[0:1], off offset:3072
	global_load_dwordx4 v[44:47], v[2:3], off
	global_load_dwordx4 v[40:43], v[2:3], off offset:64
	global_load_dwordx4 v[36:39], v[2:3], off offset:128
	global_load_dwordx4 v[32:35], v[2:3], off offset:192
	v_readlane_b32 s18, v238, 34
	v_readlane_b32 s19, v238, 35
	v_readlane_b32 s20, v238, 36
	v_readlane_b32 s21, v238, 37
	v_readlane_b32 s22, v238, 38
	v_readlane_b32 s23, v238, 39
	v_readlane_b32 s24, v238, 40
	v_readlane_b32 s25, v238, 41
	v_readlane_b32 s26, v238, 42
	v_readlane_b32 s27, v238, 43
	v_readlane_b32 s28, v238, 44
	v_readlane_b32 s29, v238, 45
	v_readlane_b32 s30, v238, 46
	v_readlane_b32 s31, v238, 47
	v_readlane_b32 s37, v236, 33
	v_readlane_b32 s38, v236, 34
	v_readlane_b32 s39, v236, 35
	v_readlane_b32 s40, v236, 36
	v_readlane_b32 s41, v236, 37
	v_readlane_b32 s42, v236, 38
	v_readlane_b32 s43, v236, 39
	v_readlane_b32 s44, v236, 40
	v_readlane_b32 s45, v236, 41
	v_readlane_b32 s48, v236, 44
	v_readlane_b32 s49, v236, 45
	v_readlane_b32 s50, v236, 46
	v_readlane_b32 s51, v236, 47
	s_waitcnt vmcnt(12)
	v_mul_f32_e32 v1, v90, v89
	v_mul_f32_e32 v0, v89, v89
	s_waitcnt vmcnt(10)
	v_mul_f32_e32 v3, v83, v82
	v_mul_f32_e32 v2, v82, v82
	v_fma_f32 v91, v1, 2.0, 0
	v_fma_f32 v84, v3, 2.0, 0
	v_fma_f32 v92, v90, v90, -v0
	v_fma_f32 v85, v83, v83, -v2
	v_mul_f32_e32 v0, v89, v91
	v_mul_f32_e32 v16, v90, v91
	v_mul_f32_e32 v3, v82, v84
	v_mul_f32_e32 v17, v83, v84
	v_mul_f32_e32 v18, v84, v84
	v_mul_f32_e32 v19, v85, v84
	v_fma_f32 v20, v90, v92, -v0
	v_fmac_f32_e32 v16, v89, v92
	v_fma_f32 v21, v83, v85, -v3
	v_fmac_f32_e32 v17, v82, v85
	v_mul_f32_e32 v1, v91, v91
	v_mul_f32_e32 v2, v92, v91
	v_fma_f32 v77, v85, v85, -v18
	v_fma_f32 v78, v19, 2.0, 0
	v_add_f32_e32 v94, 0, v20
	v_add_f32_e32 v93, 0, v16
	v_add_f32_e32 v87, 0, v21
	v_add_f32_e32 v86, 0, v17
	s_waitcnt vmcnt(7)
	v_mfma_f32_32x32x16_bf16 v[16:31], v[64:67], v[56:59], 0
	v_fma_f32 v79, v92, v92, -v1
	v_fma_f32 v80, v2, 2.0, 0
	v_mul_f32_e32 v183, v68, v80
	v_fma_f32 v183, v70, v79, -v183
	v_mfma_f32_32x32x16_bf16 v[0:15], v[64:67], v[60:63], 0
	s_nop 6
	v_mul_f32_e32 v73, v89, v16
	v_mul_f32_e32 v139, v90, v16
	v_mul_f32_e32 v178, v90, v24
	v_mul_f32_e32 v145, v89, v24
	v_mul_f32_e32 v143, v89, v20
	v_mul_f32_e32 v144, v90, v20
	v_fma_f32 v73, v90, v0, -v73
	v_fmac_f32_e32 v139, v89, v0
	v_add_f32_e32 v1, v1, v73
	v_add_f32_e32 v17, v17, v139
	v_mul_f32_e32 v139, v89, v1
	v_mul_f32_e32 v73, v89, v17
	v_fmac_f32_e32 v139, v90, v17
	v_fma_f32 v73, v90, v1, -v73
	v_add_f32_e32 v18, v18, v139
	v_add_f32_e32 v2, v2, v73
	v_mul_f32_e32 v73, v89, v18
	v_fmac_f32_e32 v178, v89, v8
	v_fma_f32 v145, v90, v8, -v145
	v_fma_f32 v73, v90, v2, -v73
	v_add_f32_e32 v25, v25, v178
	v_add_f32_e32 v9, v9, v145
	v_add_f32_e32 v3, v3, v73
	v_mul_f32_e32 v73, v89, v25
	v_fma_f32 v73, v90, v9, -v73
	v_add_f32_e32 v10, v10, v73
	v_mul_f32_e32 v73, v89, v9
	v_fmac_f32_e32 v73, v90, v25
	v_add_f32_e32 v26, v26, v73
	v_mul_f32_e32 v73, v89, v26
	v_fma_f32 v73, v90, v10, -v73
	v_add_f32_e32 v11, v11, v73
	v_mul_f32_e32 v73, v89, v10
	v_fmac_f32_e32 v73, v90, v26
	v_add_f32_e32 v27, v27, v73
	v_mul_f32_e32 v73, v89, v28
	v_fma_f32 v73, v90, v12, -v73
	v_add_f32_e32 v13, v13, v73
	v_mul_f32_e32 v73, v90, v28
	v_fmac_f32_e32 v73, v89, v12
	v_add_f32_e32 v29, v29, v73
	v_mul_f32_e32 v73, v89, v29
	v_fma_f32 v73, v90, v13, -v73
	v_fma_f32 v143, v90, v4, -v143
	v_add_f32_e32 v14, v14, v73
	v_mul_f32_e32 v73, v89, v13
	v_fmac_f32_e32 v144, v89, v4
	v_add_f32_e32 v5, v5, v143
	v_fmac_f32_e32 v73, v90, v29
	v_add_f32_e32 v21, v21, v144
	v_mul_f32_e32 v144, v89, v5
	v_add_f32_e32 v30, v30, v73
	v_mul_f32_e32 v143, v89, v21
	v_fmac_f32_e32 v144, v90, v21
	v_mul_f32_e32 v139, v89, v2
	v_mul_f32_e32 v73, v89, v30
	v_fma_f32 v143, v90, v5, -v143
	v_add_f32_e32 v22, v22, v144
	v_fmac_f32_e32 v139, v90, v18
	v_fma_f32 v73, v90, v14, -v73
	v_add_f32_e32 v6, v6, v143
	v_mul_f32_e32 v143, v89, v22
	v_add_f32_e32 v19, v19, v139
	v_add_f32_e32 v139, v15, v73
	v_mul_f32_e32 v15, v89, v14
	v_fma_f32 v143, v90, v6, -v143
	v_fmac_f32_e32 v15, v90, v30
	v_add_f32_e32 v7, v7, v143
	v_add_f32_e32 v143, v31, v15
	ds_bpermute_b32 v15, v88, v3
	ds_bpermute_b32 v31, v88, v19
	v_mul_f32_e32 v144, v89, v6
	v_fmac_f32_e32 v144, v90, v22
	ds_bpermute_b32 v73, v88, v7
	s_waitcnt lgkmcnt(2)
	v_cndmask_b32_e64 v181, v15, v3, s[4:5]
	v_add_f32_e32 v181, v183, v181
	v_mul_f32_e32 v183, v70, v80
	s_waitcnt lgkmcnt(1)
	v_cndmask_b32_e64 v182, v31, v19, s[4:5]
	v_fmac_f32_e32 v183, v68, v79
	v_add_f32_e32 v182, v183, v182
	v_mul_f32_e32 v183, v80, v182
	v_cndmask_b32_e64 v15, v3, v15, s[4:5]
	v_fma_f32 v183, v79, v181, -v183
	v_add_f32_e32 v23, v23, v144
	v_add_f32_e32 v15, v15, v183
	v_mul_f32_e32 v183, v80, v181
	ds_bpermute_b32 v178, v88, v23
	v_cndmask_b32_e64 v31, v19, v31, s[4:5]
	v_fmac_f32_e32 v183, v79, v182
	v_add_f32_e32 v31, v31, v183
	v_mul_f32_e32 v183, v80, v31
	v_cndmask_b32_e64 v70, v181, v70, s[4:5]
	s_waitcnt lgkmcnt(1)
	v_cndmask_b32_e64 v181, v73, v7, s[4:5]
	v_fma_f32 v183, v79, v15, -v183
	v_add_f32_e32 v181, v181, v183
	v_mul_f32_e32 v183, v80, v15
	v_cndmask_b32_e64 v68, v182, v68, s[4:5]
	s_waitcnt lgkmcnt(0)
	v_cndmask_b32_e64 v182, v178, v23, s[4:5]
	v_fmac_f32_e32 v183, v79, v31
	v_add_f32_e32 v182, v182, v183
	v_mul_f32_e32 v183, v80, v182
	ds_bpermute_b32 v179, v88, v11
	v_cndmask_b32_e64 v73, v7, v73, s[4:5]
	v_fma_f32 v183, v79, v181, -v183
	v_add_f32_e32 v73, v73, v183
	v_mul_f32_e32 v183, v80, v181
	ds_bpermute_b32 v180, v88, v27
	v_cndmask_b32_e64 v178, v23, v178, s[4:5]
	v_fmac_f32_e32 v183, v79, v182
	v_add_f32_e32 v178, v178, v183
	v_mul_f32_e32 v183, v80, v178
	v_cndmask_b32_e64 v15, v181, v15, s[4:5]
	s_waitcnt lgkmcnt(1)
	v_cndmask_b32_e64 v181, v179, v11, s[4:5]
	v_fma_f32 v183, v79, v73, -v183
	v_add_f32_e32 v181, v181, v183
	v_mul_f32_e32 v183, v80, v73
	v_cndmask_b32_e64 v31, v182, v31, s[4:5]
	s_waitcnt lgkmcnt(0)
	v_cndmask_b32_e64 v182, v180, v27, s[4:5]
	v_fmac_f32_e32 v183, v79, v178
	v_add_f32_e32 v182, v182, v183
	ds_bpermute_b32 v145, v88, v143
	v_mul_f32_e32 v183, v80, v182
	ds_bpermute_b32 v144, v88, v139
	v_cndmask_b32_e64 v179, v11, v179, s[4:5]
	v_fma_f32 v183, v79, v181, -v183
	v_add_f32_e32 v183, v179, v183
	v_mul_f32_e32 v179, v80, v181
	v_cndmask_b32_e64 v180, v27, v180, s[4:5]
	v_fmac_f32_e32 v179, v79, v182
	v_add_f32_e32 v180, v180, v179
	v_mul_f32_e32 v179, v80, v183
	v_cndmask_b32_e64 v73, v181, v73, s[4:5]
	v_cndmask_b32_e64 v181, v182, v178, s[4:5]
	s_waitcnt lgkmcnt(1)
	v_cndmask_b32_e64 v178, v145, v143, s[4:5]
	v_fmac_f32_e32 v179, v79, v180
	v_mul_f32_e32 v182, v80, v180
	v_add_f32_e32 v178, v178, v179
	s_waitcnt lgkmcnt(0)
	v_cndmask_b32_e64 v179, v144, v139, s[4:5]
	v_fma_f32 v182, v79, v183, -v182
	v_add_f32_e32 v179, v179, v182
	v_cndmask_b32_e64 v182, v179, v183, s[4:5]
	v_mul_f32_e32 v183, v89, v68
	v_fma_f32 v183, v90, v70, -v183
	v_add_f32_e32 v0, v0, v183
	v_mul_f32_e32 v183, v90, v68
	v_fmac_f32_e32 v183, v89, v70
	v_add_f32_e32 v16, v16, v183
	v_bfe_u32 v183, v0, 16, 1
	v_add3_u32 v0, v0, v183, s83
	ds_write_b16_d16_hi v163, v0
	v_bfe_u32 v0, v16, 16, 1
	v_add3_u32 v0, v16, v0, s83
	ds_write_b16_d16_hi v163, v0 offset:128
	v_mul_f32_e32 v0, v91, v68
	v_fma_f32 v0, v92, v70, -v0
	v_add_f32_e32 v0, v1, v0
	v_mul_f32_e32 v1, v92, v68
	v_fmac_f32_e32 v1, v91, v70
	v_bfe_u32 v16, v0, 16, 1
	v_add_f32_e32 v1, v17, v1
	v_add3_u32 v0, v0, v16, s83
	ds_write_b16_d16_hi v163, v0 offset:272
	v_bfe_u32 v0, v1, 16, 1
	v_add3_u32 v0, v1, v0, s83
	ds_write_b16_d16_hi v163, v0 offset:400
	v_mul_f32_e32 v0, v93, v68
	v_fma_f32 v0, v94, v70, -v0
	v_add_f32_e32 v0, v2, v0
	v_mul_f32_e32 v1, v94, v68
	v_fmac_f32_e32 v1, v93, v70
	v_bfe_u32 v2, v0, 16, 1
	v_add_f32_e32 v1, v18, v1
	v_add3_u32 v0, v0, v2, s83
	ds_write_b16_d16_hi v163, v0 offset:544
	v_bfe_u32 v0, v1, 16, 1
	v_add3_u32 v0, v1, v0, s83
	ds_write_b16_d16_hi v163, v0 offset:672
	v_mul_f32_e32 v0, v80, v68
	v_fma_f32 v0, v79, v70, -v0
	v_add_f32_e32 v0, v3, v0
	v_mul_f32_e32 v1, v79, v68
	v_fmac_f32_e32 v1, v80, v70
	v_bfe_u32 v2, v0, 16, 1
	v_add_f32_e32 v1, v19, v1
	v_add3_u32 v0, v0, v2, s83
	ds_write_b16_d16_hi v163, v0 offset:816
	v_bfe_u32 v0, v1, 16, 1
	v_add3_u32 v0, v1, v0, s83
	ds_write_b16_d16_hi v163, v0 offset:944
	v_mul_f32_e32 v0, v89, v31
	v_fma_f32 v0, v90, v15, -v0
	v_add_f32_e32 v0, v4, v0
	v_mul_f32_e32 v1, v90, v31
	v_fmac_f32_e32 v1, v89, v15
	v_bfe_u32 v2, v0, 16, 1
	v_add_f32_e32 v1, v20, v1
	v_add3_u32 v0, v0, v2, s83
	ds_write_b16_d16_hi v163, v0 offset:2176
	v_bfe_u32 v0, v1, 16, 1
	v_add3_u32 v0, v1, v0, s83
	ds_write_b16_d16_hi v163, v0 offset:2304
	v_mul_f32_e32 v0, v91, v31
	v_fma_f32 v0, v92, v15, -v0
	v_add_f32_e32 v0, v5, v0
	v_mul_f32_e32 v1, v92, v31
	v_fmac_f32_e32 v1, v91, v15
	v_bfe_u32 v2, v0, 16, 1
	v_add_f32_e32 v1, v21, v1
	v_add3_u32 v0, v0, v2, s83
	ds_write_b16_d16_hi v163, v0 offset:2448
	v_bfe_u32 v0, v1, 16, 1
	v_add3_u32 v0, v1, v0, s83
	ds_write_b16_d16_hi v163, v0 offset:2576
	v_mul_f32_e32 v0, v93, v31
	v_fma_f32 v0, v94, v15, -v0
	v_add_f32_e32 v0, v6, v0
	v_mul_f32_e32 v1, v94, v31
	v_fmac_f32_e32 v1, v93, v15
	v_bfe_u32 v2, v0, 16, 1
	v_add_f32_e32 v1, v22, v1
	v_add3_u32 v0, v0, v2, s83
	ds_write_b16_d16_hi v163, v0 offset:2720
	v_bfe_u32 v0, v1, 16, 1
	v_add3_u32 v0, v1, v0, s83
	ds_write_b16_d16_hi v163, v0 offset:2848
	v_mul_f32_e32 v0, v80, v31
	v_fma_f32 v0, v79, v15, -v0
	v_add_f32_e32 v0, v7, v0
	v_mul_f32_e32 v1, v79, v31
	v_fmac_f32_e32 v1, v80, v15
	v_bfe_u32 v2, v0, 16, 1
	v_add_f32_e32 v1, v23, v1
	v_add3_u32 v0, v0, v2, s83
	ds_write_b16_d16_hi v163, v0 offset:2992
	v_bfe_u32 v0, v1, 16, 1
	v_add3_u32 v0, v1, v0, s83
	ds_write_b16_d16_hi v163, v0 offset:3120
	v_mul_f32_e32 v0, v89, v181
	v_fma_f32 v0, v90, v73, -v0
	v_add_f32_e32 v0, v8, v0
	v_mul_f32_e32 v1, v90, v181
	v_fmac_f32_e32 v1, v89, v73
	v_bfe_u32 v2, v0, 16, 1
	v_add_f32_e32 v1, v24, v1
	v_add3_u32 v0, v0, v2, s83
	ds_write_b16_d16_hi v163, v0 offset:4352
	v_bfe_u32 v0, v1, 16, 1
	v_add3_u32 v0, v1, v0, s83
	ds_write_b16_d16_hi v163, v0 offset:4480
	v_mul_f32_e32 v0, v91, v181
	v_fma_f32 v0, v92, v73, -v0
	v_add_f32_e32 v0, v9, v0
	v_mul_f32_e32 v1, v92, v181
	v_fmac_f32_e32 v1, v91, v73
	v_bfe_u32 v2, v0, 16, 1
	v_add_f32_e32 v1, v25, v1
	v_add3_u32 v0, v0, v2, s83
	ds_write_b16_d16_hi v163, v0 offset:4624
	v_bfe_u32 v0, v1, 16, 1
	v_add3_u32 v0, v1, v0, s83
	ds_write_b16_d16_hi v163, v0 offset:4752
	v_mul_f32_e32 v0, v93, v181
	v_fma_f32 v0, v94, v73, -v0
	v_add_f32_e32 v0, v10, v0
	v_mul_f32_e32 v1, v94, v181
	v_fmac_f32_e32 v1, v93, v73
	v_bfe_u32 v2, v0, 16, 1
	v_add_f32_e32 v1, v26, v1
	v_add3_u32 v0, v0, v2, s83
	ds_write_b16_d16_hi v163, v0 offset:4896
	v_bfe_u32 v0, v1, 16, 1
	v_add3_u32 v0, v1, v0, s83
	ds_write_b16_d16_hi v163, v0 offset:5024
	v_mul_f32_e32 v0, v80, v181
	v_fma_f32 v0, v79, v73, -v0
	v_add_f32_e32 v0, v11, v0
	v_mul_f32_e32 v1, v79, v181
	v_fmac_f32_e32 v1, v80, v73
	v_bfe_u32 v2, v0, 16, 1
	v_add_f32_e32 v1, v27, v1
	v_add3_u32 v0, v0, v2, s83
	ds_write_b16_d16_hi v163, v0 offset:5168
	v_bfe_u32 v0, v1, 16, 1
	v_cndmask_b32_e64 v180, v178, v180, s[4:5]
	v_add3_u32 v0, v1, v0, s83
	ds_write_b16_d16_hi v163, v0 offset:5296
	v_mul_f32_e32 v0, v89, v180
	v_fma_f32 v0, v90, v182, -v0
	v_add_f32_e32 v0, v12, v0
	v_mul_f32_e32 v1, v90, v180
	v_fmac_f32_e32 v1, v89, v182
	v_bfe_u32 v2, v0, 16, 1
	v_add_f32_e32 v1, v28, v1
	v_add3_u32 v0, v0, v2, s83
	ds_write_b16_d16_hi v163, v0 offset:6528
	v_bfe_u32 v0, v1, 16, 1
	v_add3_u32 v0, v1, v0, s83
	ds_write_b16_d16_hi v163, v0 offset:6656
	v_mul_f32_e32 v0, v91, v180
	v_fma_f32 v0, v92, v182, -v0
	v_add_f32_e32 v0, v13, v0
	v_mul_f32_e32 v1, v92, v180
	v_fmac_f32_e32 v1, v91, v182
	v_bfe_u32 v2, v0, 16, 1
	v_add_f32_e32 v1, v29, v1
	v_add3_u32 v0, v0, v2, s83
	ds_write_b16_d16_hi v163, v0 offset:6800
	v_bfe_u32 v0, v1, 16, 1
	v_add3_u32 v0, v1, v0, s83
	ds_write_b16_d16_hi v163, v0 offset:6928
	v_mul_f32_e32 v0, v93, v180
	v_fma_f32 v0, v94, v182, -v0
	v_add_f32_e32 v0, v14, v0
	v_mul_f32_e32 v1, v94, v180
	v_fmac_f32_e32 v1, v93, v182
	v_bfe_u32 v2, v0, 16, 1
	v_add_f32_e32 v1, v30, v1
	v_add3_u32 v0, v0, v2, s83
	ds_write_b16_d16_hi v163, v0 offset:7072
	v_bfe_u32 v0, v1, 16, 1
	v_add3_u32 v0, v1, v0, s83
	ds_write_b16_d16_hi v163, v0 offset:7200
	v_mul_f32_e32 v0, v80, v180
	v_fma_f32 v0, v79, v182, -v0
	v_add_f32_e32 v16, v139, v0
	v_mul_f32_e32 v17, v79, v180
	v_fmac_f32_e32 v17, v80, v182
	v_bfe_u32 v18, v16, 16, 1
	v_add_f32_e32 v17, v143, v17
	v_add3_u32 v16, v16, v18, s83
	ds_write_b16_d16_hi v163, v16 offset:7344
	v_bfe_u32 v16, v17, 16, 1
	v_add3_u32 v16, v17, v16, s83
	ds_write_b16_d16_hi v163, v16 offset:7472
	s_waitcnt vmcnt(4)
	v_mfma_f32_32x32x16_bf16 v[16:31], v[64:67], v[48:51], 0
	v_mul_f32_e32 v183, v69, v78
	v_fma_f32 v183, v71, v77, -v183
	v_mfma_f32_32x32x16_bf16 v[0:15], v[64:67], v[52:55], 0
	s_nop 8
	v_mul_f32_e32 v64, v82, v16
	s_nop 1
	v_fma_f32 v64, v83, v0, -v64
	v_add_f32_e32 v1, v1, v64
	v_mul_f32_e32 v64, v83, v16
	v_fmac_f32_e32 v64, v82, v0
	v_add_f32_e32 v64, v17, v64
	v_mul_f32_e32 v17, v82, v64
	v_fma_f32 v17, v83, v1, -v17
	v_add_f32_e32 v2, v2, v17
	v_mul_f32_e32 v17, v82, v1
	v_fmac_f32_e32 v17, v83, v64
	v_add_f32_e32 v65, v18, v17
	v_mul_f32_e32 v17, v82, v65
	v_fma_f32 v17, v83, v2, -v17
	v_add_f32_e32 v3, v3, v17
	v_mul_f32_e32 v17, v82, v2
	v_fmac_f32_e32 v17, v83, v65
	v_add_f32_e32 v19, v19, v17
	v_mul_f32_e32 v17, v82, v20
	v_fma_f32 v17, v83, v4, -v17
	v_add_f32_e32 v5, v5, v17
	v_mul_f32_e32 v17, v83, v20
	v_fmac_f32_e32 v17, v82, v4
	v_add_f32_e32 v21, v21, v17
	v_mul_f32_e32 v17, v82, v21
	v_fma_f32 v17, v83, v5, -v17
	v_add_f32_e32 v66, v6, v17
	v_mul_f32_e32 v6, v82, v5
	v_fmac_f32_e32 v6, v83, v21
	v_add_f32_e32 v22, v22, v6
	v_mul_f32_e32 v6, v82, v22
	v_fma_f32 v6, v83, v66, -v6
	v_add_f32_e32 v67, v7, v6
	v_mul_f32_e32 v6, v82, v66
	v_fmac_f32_e32 v6, v83, v22
	v_add_f32_e32 v23, v23, v6
	v_mul_f32_e32 v6, v82, v24
	v_fma_f32 v6, v83, v8, -v6
	v_add_f32_e32 v68, v9, v6
	v_mul_f32_e32 v6, v83, v24
	v_fmac_f32_e32 v6, v82, v8
	v_add_f32_e32 v25, v25, v6
	v_mul_f32_e32 v6, v82, v25
	v_fma_f32 v6, v83, v68, -v6
	v_add_f32_e32 v70, v10, v6
	v_mul_f32_e32 v6, v82, v68
	v_fmac_f32_e32 v6, v83, v25
	v_add_f32_e32 v26, v26, v6
	v_mul_f32_e32 v6, v82, v26
	v_fma_f32 v6, v83, v70, -v6
	v_add_f32_e32 v11, v11, v6
	v_mul_f32_e32 v6, v82, v70
	v_fmac_f32_e32 v6, v83, v26
	v_add_f32_e32 v27, v27, v6
	v_mul_f32_e32 v6, v82, v28
	v_fma_f32 v6, v83, v12, -v6
	v_add_f32_e32 v13, v13, v6
	v_mul_f32_e32 v6, v83, v28
	v_fmac_f32_e32 v6, v82, v12
	v_add_f32_e32 v29, v29, v6
	v_mul_f32_e32 v6, v82, v29
	v_fma_f32 v6, v83, v13, -v6
	v_add_f32_e32 v14, v14, v6
	v_mul_f32_e32 v6, v82, v13
	v_fmac_f32_e32 v6, v83, v29
	v_add_f32_e32 v30, v30, v6
	v_mul_f32_e32 v6, v82, v30
	v_fma_f32 v6, v83, v14, -v6
	v_add_f32_e32 v6, v15, v6
	ds_bpermute_b32 v15, v88, v3
	ds_bpermute_b32 v17, v88, v19
	v_mul_f32_e32 v7, v82, v14
	ds_bpermute_b32 v18, v88, v67
	v_fmac_f32_e32 v7, v83, v30
	s_waitcnt lgkmcnt(2)
	v_cndmask_b32_e64 v181, v15, v3, s[4:5]
	v_add_f32_e32 v181, v183, v181
	v_mul_f32_e32 v183, v71, v78
	s_waitcnt lgkmcnt(1)
	v_cndmask_b32_e64 v182, v17, v19, s[4:5]
	v_fmac_f32_e32 v183, v69, v77
	v_add_f32_e32 v182, v183, v182
	v_mul_f32_e32 v183, v78, v182
	v_cndmask_b32_e64 v15, v3, v15, s[4:5]
	v_fma_f32 v183, v77, v181, -v183
	v_add_f32_e32 v15, v15, v183
	v_mul_f32_e32 v183, v78, v181
	v_add_f32_e32 v7, v31, v7
	ds_bpermute_b32 v31, v88, v23
	v_cndmask_b32_e64 v17, v19, v17, s[4:5]
	v_fmac_f32_e32 v183, v77, v182
	v_add_f32_e32 v17, v17, v183
	v_mul_f32_e32 v183, v78, v17
	v_cndmask_b32_e64 v71, v181, v71, s[4:5]
	s_waitcnt lgkmcnt(1)
	v_cndmask_b32_e64 v181, v18, v67, s[4:5]
	v_fma_f32 v183, v77, v15, -v183
	v_add_f32_e32 v181, v181, v183
	v_mul_f32_e32 v183, v78, v15
	v_cndmask_b32_e64 v69, v182, v69, s[4:5]
	s_waitcnt lgkmcnt(0)
	v_cndmask_b32_e64 v182, v31, v23, s[4:5]
	v_fmac_f32_e32 v183, v77, v17
	v_add_f32_e32 v182, v182, v183
	v_mul_f32_e32 v183, v78, v182
	ds_bpermute_b32 v73, v88, v11
	v_cndmask_b32_e64 v18, v67, v18, s[4:5]
	v_fma_f32 v183, v77, v181, -v183
	v_add_f32_e32 v18, v18, v183
	v_mul_f32_e32 v183, v78, v181
	ds_bpermute_b32 v180, v88, v27
	v_cndmask_b32_e64 v31, v23, v31, s[4:5]
	v_fmac_f32_e32 v183, v77, v182
	v_add_f32_e32 v31, v31, v183
	v_mul_f32_e32 v183, v78, v31
	v_cndmask_b32_e64 v15, v181, v15, s[4:5]
	v_cndmask_b32_e64 v181, v182, v17, s[4:5]
	s_waitcnt lgkmcnt(1)
	v_cndmask_b32_e64 v17, v73, v11, s[4:5]
	v_fma_f32 v183, v77, v18, -v183
	v_add_f32_e32 v17, v17, v183
	v_mul_f32_e32 v183, v78, v18
	s_waitcnt lgkmcnt(0)
	v_cndmask_b32_e64 v182, v180, v27, s[4:5]
	v_fmac_f32_e32 v183, v77, v31
	v_add_f32_e32 v182, v182, v183
	ds_bpermute_b32 v10, v88, v7
	v_mul_f32_e32 v183, v78, v182
	ds_bpermute_b32 v9, v88, v6
	v_cndmask_b32_e64 v73, v11, v73, s[4:5]
	v_fma_f32 v183, v77, v17, -v183
	v_add_f32_e32 v73, v73, v183
	v_mul_f32_e32 v183, v78, v17
	v_cndmask_b32_e64 v180, v27, v180, s[4:5]
	v_fmac_f32_e32 v183, v77, v182
	v_add_f32_e32 v180, v180, v183
	v_cndmask_b32_e64 v183, v17, v18, s[4:5]
	v_mul_f32_e32 v18, v78, v73
	v_cndmask_b32_e64 v31, v182, v31, s[4:5]
	s_waitcnt lgkmcnt(1)
	v_cndmask_b32_e64 v17, v10, v7, s[4:5]
	v_fmac_f32_e32 v18, v77, v180
	v_mul_f32_e32 v182, v78, v180
	v_add_f32_e32 v17, v17, v18
	s_waitcnt lgkmcnt(0)
	v_cndmask_b32_e64 v18, v9, v6, s[4:5]
	v_fma_f32 v182, v77, v73, -v182
	v_add_f32_e32 v18, v18, v182
	v_mul_f32_e32 v182, v82, v69
	v_fma_f32 v182, v83, v71, -v182
	v_add_f32_e32 v0, v0, v182
	v_mul_f32_e32 v182, v83, v69
	v_fmac_f32_e32 v182, v82, v71
	v_add_f32_e32 v16, v16, v182
	v_bfe_u32 v182, v0, 16, 1
	v_add3_u32 v0, v0, v182, s83
	ds_write_b16_d16_hi v164, v0
	v_bfe_u32 v0, v16, 16, 1
	v_add3_u32 v0, v16, v0, s83
	ds_write_b16_d16_hi v165, v0
	v_mul_f32_e32 v0, v84, v69
	v_fma_f32 v0, v85, v71, -v0
	v_add_f32_e32 v0, v1, v0
	v_mul_f32_e32 v1, v85, v69
	v_fmac_f32_e32 v1, v84, v71
	v_bfe_u32 v16, v0, 16, 1
	v_add_f32_e32 v1, v64, v1
	v_add3_u32 v0, v0, v16, s83
	ds_write_b16_d16_hi v164, v0 offset:272
	v_bfe_u32 v0, v1, 16, 1
	v_add3_u32 v0, v1, v0, s83
	ds_write_b16_d16_hi v165, v0 offset:272
	v_mul_f32_e32 v0, v86, v69
	v_fma_f32 v0, v87, v71, -v0
	v_add_f32_e32 v0, v2, v0
	v_mul_f32_e32 v1, v87, v69
	v_fmac_f32_e32 v1, v86, v71
	v_bfe_u32 v2, v0, 16, 1
	v_add_f32_e32 v1, v65, v1
	v_add3_u32 v0, v0, v2, s83
	ds_write_b16_d16_hi v164, v0 offset:544
	v_bfe_u32 v0, v1, 16, 1
	v_add3_u32 v0, v1, v0, s83
	ds_write_b16_d16_hi v165, v0 offset:544
	v_mul_f32_e32 v0, v78, v69
	v_fma_f32 v0, v77, v71, -v0
	v_add_f32_e32 v0, v3, v0
	v_mul_f32_e32 v1, v77, v69
	v_fmac_f32_e32 v1, v78, v71
	v_bfe_u32 v2, v0, 16, 1
	v_add_f32_e32 v1, v19, v1
	v_add3_u32 v0, v0, v2, s83
	ds_write_b16_d16_hi v164, v0 offset:816
	v_bfe_u32 v0, v1, 16, 1
	v_add3_u32 v0, v1, v0, s83
	ds_write_b16_d16_hi v165, v0 offset:816
	v_mul_f32_e32 v0, v82, v181
	v_fma_f32 v0, v83, v15, -v0
	v_add_f32_e32 v0, v4, v0
	v_mul_f32_e32 v1, v83, v181
	v_fmac_f32_e32 v1, v82, v15
	v_bfe_u32 v2, v0, 16, 1
	v_add_f32_e32 v1, v20, v1
	v_add3_u32 v0, v0, v2, s83
	ds_write_b16_d16_hi v164, v0 offset:2176
	v_bfe_u32 v0, v1, 16, 1
	v_add3_u32 v0, v1, v0, s83
	ds_write_b16_d16_hi v165, v0 offset:2176
	v_mul_f32_e32 v0, v84, v181
	v_fma_f32 v0, v85, v15, -v0
	v_add_f32_e32 v0, v5, v0
	v_mul_f32_e32 v1, v85, v181
	v_fmac_f32_e32 v1, v84, v15
	v_bfe_u32 v2, v0, 16, 1
	v_add_f32_e32 v1, v21, v1
	v_add3_u32 v0, v0, v2, s83
	ds_write_b16_d16_hi v164, v0 offset:2448
	v_bfe_u32 v0, v1, 16, 1
	v_add3_u32 v0, v1, v0, s83
	ds_write_b16_d16_hi v165, v0 offset:2448
	v_mul_f32_e32 v0, v86, v181
	v_fma_f32 v0, v87, v15, -v0
	v_add_f32_e32 v0, v66, v0
	v_mul_f32_e32 v1, v87, v181
	v_fmac_f32_e32 v1, v86, v15
	v_bfe_u32 v2, v0, 16, 1
	v_add_f32_e32 v1, v22, v1
	v_add3_u32 v0, v0, v2, s83
	ds_write_b16_d16_hi v164, v0 offset:2720
	v_bfe_u32 v0, v1, 16, 1
	v_add3_u32 v0, v1, v0, s83
	ds_write_b16_d16_hi v165, v0 offset:2720
	v_mul_f32_e32 v0, v78, v181
	v_fma_f32 v0, v77, v15, -v0
	v_add_f32_e32 v0, v67, v0
	v_mul_f32_e32 v1, v77, v181
	v_fmac_f32_e32 v1, v78, v15
	v_bfe_u32 v2, v0, 16, 1
	v_add_f32_e32 v1, v23, v1
	v_add3_u32 v0, v0, v2, s83
	ds_write_b16_d16_hi v164, v0 offset:2992
	v_bfe_u32 v0, v1, 16, 1
	v_add3_u32 v0, v1, v0, s83
	ds_write_b16_d16_hi v165, v0 offset:2992
	v_mul_f32_e32 v0, v82, v31
	v_fma_f32 v0, v83, v183, -v0
	v_add_f32_e32 v0, v8, v0
	v_mul_f32_e32 v1, v83, v31
	v_fmac_f32_e32 v1, v82, v183
	v_bfe_u32 v2, v0, 16, 1
	v_add_f32_e32 v1, v24, v1
	v_add3_u32 v0, v0, v2, s83
	ds_write_b16_d16_hi v164, v0 offset:4352
	v_bfe_u32 v0, v1, 16, 1
	v_add3_u32 v0, v1, v0, s83
	ds_write_b16_d16_hi v165, v0 offset:4352
	v_mul_f32_e32 v0, v84, v31
	v_fma_f32 v0, v85, v183, -v0
	v_add_f32_e32 v0, v68, v0
	v_mul_f32_e32 v1, v85, v31
	v_fmac_f32_e32 v1, v84, v183
	v_bfe_u32 v2, v0, 16, 1
	v_add_f32_e32 v1, v25, v1
	v_add3_u32 v0, v0, v2, s83
	ds_write_b16_d16_hi v164, v0 offset:4624
	v_bfe_u32 v0, v1, 16, 1
	v_add3_u32 v0, v1, v0, s83
	ds_write_b16_d16_hi v165, v0 offset:4624
	v_mul_f32_e32 v0, v86, v31
	v_fma_f32 v0, v87, v183, -v0
	v_add_f32_e32 v0, v70, v0
	v_mul_f32_e32 v1, v87, v31
	v_fmac_f32_e32 v1, v86, v183
	v_bfe_u32 v2, v0, 16, 1
	v_add_f32_e32 v1, v26, v1
	v_add3_u32 v0, v0, v2, s83
	ds_write_b16_d16_hi v164, v0 offset:4896
	v_bfe_u32 v0, v1, 16, 1
	v_add3_u32 v0, v1, v0, s83
	ds_write_b16_d16_hi v165, v0 offset:4896
	v_mul_f32_e32 v0, v78, v31
	v_fma_f32 v0, v77, v183, -v0
	v_add_f32_e32 v0, v11, v0
	v_mul_f32_e32 v1, v77, v31
	v_fmac_f32_e32 v1, v78, v183
	v_bfe_u32 v2, v0, 16, 1
	v_add_f32_e32 v1, v27, v1
	v_add3_u32 v0, v0, v2, s83
	ds_write_b16_d16_hi v164, v0 offset:5168
	v_bfe_u32 v0, v1, 16, 1
	v_cndmask_b32_e64 v180, v17, v180, s[4:5]
	v_add3_u32 v0, v1, v0, s83
	v_cndmask_b32_e64 v73, v18, v73, s[4:5]
	ds_write_b16_d16_hi v165, v0 offset:5168
	v_mul_f32_e32 v0, v82, v180
	v_fma_f32 v0, v83, v73, -v0
	v_add_f32_e32 v0, v12, v0
	v_mul_f32_e32 v1, v83, v180
	v_fmac_f32_e32 v1, v82, v73
	v_bfe_u32 v2, v0, 16, 1
	v_add_f32_e32 v1, v28, v1
	v_add3_u32 v0, v0, v2, s83
	ds_write_b16_d16_hi v164, v0 offset:6528
	v_bfe_u32 v0, v1, 16, 1
	v_add3_u32 v0, v1, v0, s83
	ds_write_b16_d16_hi v165, v0 offset:6528
	v_mul_f32_e32 v0, v84, v180
	v_fma_f32 v0, v85, v73, -v0
	v_add_f32_e32 v0, v13, v0
	v_mul_f32_e32 v1, v85, v180
	v_fmac_f32_e32 v1, v84, v73
	v_bfe_u32 v2, v0, 16, 1
	v_add_f32_e32 v1, v29, v1
	v_add3_u32 v0, v0, v2, s83
	ds_write_b16_d16_hi v164, v0 offset:6800
	v_bfe_u32 v0, v1, 16, 1
	v_add3_u32 v0, v1, v0, s83
	ds_write_b16_d16_hi v165, v0 offset:6800
	v_mul_f32_e32 v0, v86, v180
	v_fma_f32 v0, v87, v73, -v0
	v_add_f32_e32 v0, v14, v0
	v_mul_f32_e32 v1, v87, v180
	v_fmac_f32_e32 v1, v86, v73
	v_bfe_u32 v2, v0, 16, 1
	v_add_f32_e32 v1, v30, v1
	v_add3_u32 v0, v0, v2, s83
	ds_write_b16_d16_hi v164, v0 offset:7072
	v_bfe_u32 v0, v1, 16, 1
	v_add3_u32 v0, v1, v0, s83
	ds_write_b16_d16_hi v165, v0 offset:7072
	v_mul_f32_e32 v0, v78, v180
	v_fma_f32 v0, v77, v73, -v0
	v_add_f32_e32 v0, v6, v0
	v_mul_f32_e32 v1, v77, v180
	v_fmac_f32_e32 v1, v78, v73
	v_bfe_u32 v2, v0, 16, 1
	v_add_f32_e32 v1, v7, v1
	v_add3_u32 v0, v0, v2, s83
	ds_write_b16_d16_hi v164, v0 offset:7344
	v_bfe_u32 v0, v1, 16, 1
	v_or_b32_e32 v70, v72, v166
	v_lshl_add_u64 v[68:69], v[126:127], 0, v[112:113]
	v_add3_u32 v0, v1, v0, s83
	v_mad_i64_i32 v[4:5], s[14:15], v70, s82, v[68:69]
	ds_write_b16_d16_hi v165, v0 offset:7344
	ds_read_b128 v[0:3], v173
	ds_read_b128 v[12:15], v173 offset:64
	global_load_ushort v4, v[4:5], off
	s_waitcnt vmcnt(4) lgkmcnt(1)
	v_mfma_f32_16x16x32_bf16 v[0:3], v[0:3], v[44:47], 0
	ds_read_b128 v[20:23], v173 offset:128
	s_waitcnt vmcnt(0)
	v_lshlrev_b32_e32 v4, 16, v4
	s_waitcnt lgkmcnt(1)
	v_mfma_f32_16x16x32_bf16 v[0:3], v[12:15], v[40:43], v[0:3]
	ds_read_b128 v[12:15], v173 offset:192
	s_waitcnt lgkmcnt(1)
	v_mfma_f32_16x16x32_bf16 v[0:3], v[20:23], v[36:39], v[0:3]
	s_waitcnt lgkmcnt(0)
	v_mfma_f32_16x16x32_bf16 v[0:3], v[12:15], v[32:35], v[0:3]
	s_nop 7
	v_fma_f32 v0, v81, v4, v0
	v_mul_f32_e32 v4, 0x3f3504f3, v0
	v_cmp_nlt_f32_e64 s[14:15], |v4|, 1.0
	s_and_saveexec_b64 s[36:37], s[14:15]
	s_xor_b64 s[74:75], exec, s[36:37]
	s_cbranch_execz .LBB0_518
	v_fma_f32 v5, |v4|, s94, v176
	v_fma_f32 v5, |v4|, v5, s95
	v_fma_f32 v5, |v4|, v5, s96
	v_fma_f32 v5, |v4|, v5, s97
	v_fma_f32 v5, |v4|, v5, s0
	v_fma_f32 v5, |v4|, v5, s1
	v_fma_f32 v5, |v4|, v5, |v4|
	v_mul_f32_e32 v8, 0xbfb8aa3b, v5
	v_fma_f32 v11, v5, s10, -v8
	v_rndne_f32_e32 v12, v8
	v_fmac_f32_e32 v11, 0xb2a5705f, v5
	v_sub_f32_e32 v8, v8, v12
	v_add_f32_e32 v8, v8, v11
	v_cvt_i32_f32_e32 v11, v12
	v_exp_f32_e32 v8, v8
	v_cmp_nlt_f32_e32 vcc, s11, v5
	v_ldexp_f32 v8, v8, v11
	s_nop 0
	v_cndmask_b32_e32 v8, 0, v8, vcc
	v_cmp_ngt_f32_e32 vcc, s12, v5
	s_nop 1
	v_cndmask_b32_e32 v5, v177, v8, vcc
	v_sub_f32_e32 v5, 1.0, v5

	.amdhsa_kernel _Z11mega_kernel6Params
		.amdhsa_group_segment_fixed_size 75792
		.amdhsa_private_segment_fixed_size 0
		.amdhsa_kernarg_size 912
		.amdhsa_user_sgpr_count 2
		.amdhsa_user_sgpr_dispatch_ptr 0
		.amdhsa_user_sgpr_queue_ptr 0
		.amdhsa_user_sgpr_kernarg_segment_ptr 1
		.amdhsa_user_sgpr_dispatch_id 0
		.amdhsa_user_sgpr_kernarg_preload_length 0
		.amdhsa_user_sgpr_kernarg_preload_offset 0
		.amdhsa_user_sgpr_private_segment_size 0
		.amdhsa_uses_dynamic_stack 0
		.amdhsa_enable_private_segment 0
		.amdhsa_system_sgpr_workgroup_id_x 1
		.amdhsa_system_sgpr_workgroup_id_y 0
		.amdhsa_system_sgpr_workgroup_id_z 0
		.amdhsa_system_sgpr_workgroup_info 0
		.amdhsa_system_vgpr_workitem_id 2
		.amdhsa_next_free_vgpr 256
		.amdhsa_next_free_sgpr 102
		.amdhsa_accum_offset 256
		.amdhsa_reserve_vcc 1
		.amdhsa_float_round_mode_32 0
		.amdhsa_float_round_mode_16_64 0
		.amdhsa_float_denorm_mode_32 3
		.amdhsa_float_denorm_mode_16_64 3
		.amdhsa_dx10_clamp 1
		.amdhsa_ieee_mode 1
		.amdhsa_fp16_overflow 0
		.amdhsa_tg_split 0
		.amdhsa_exception_fp_ieee_invalid_op 0
		.amdhsa_exception_fp_denorm_src 0
		.amdhsa_exception_fp_ieee_div_zero 0
		.amdhsa_exception_fp_ieee_overflow 0
		.amdhsa_exception_fp_ieee_underflow 0
		.amdhsa_exception_fp_ieee_inexact 0
		.amdhsa_exception_int_div_zero 0
	.end_amdhsa_kernel

amdhsa.kernels:
  - .agpr_count:     0
    .args:
      - .offset:         0
        .size:           656
        .value_kind:     by_value
      - .offset:         656
        .size:           4
        .value_kind:     hidden_block_count_x
      - .offset:         660
        .size:           4
        .value_kind:     hidden_block_count_y
      - .offset:         664
        .size:           4
        .value_kind:     hidden_block_count_z
      - .offset:         668
        .size:           2
        .value_kind:     hidden_group_size_x
      - .offset:         670
        .size:           2
        .value_kind:     hidden_group_size_y
      - .offset:         672
        .size:           2
        .value_kind:     hidden_group_size_z
      - .offset:         674
        .size:           2
        .value_kind:     hidden_remainder_x
      - .offset:         676
        .size:           2
        .value_kind:     hidden_remainder_y
      - .offset:         678
        .size:           2
        .value_kind:     hidden_remainder_z
      - .offset:         696
        .size:           8
        .value_kind:     hidden_global_offset_x
      - .offset:         704
        .size:           8
        .value_kind:     hidden_global_offset_y
      - .offset:         712
        .size:           8
        .value_kind:     hidden_global_offset_z
      - .offset:         720
        .size:           2
        .value_kind:     hidden_grid_dims
      - .offset:         744
        .size:           8
        .value_kind:     hidden_multigrid_sync_arg
    .group_segment_fixed_size: 75792
    .kernarg_segment_align: 8
    .kernarg_segment_size: 912
    .language:       OpenCL C
    .language_version:
      - 2
      - 0
    .max_flat_workgroup_size: 256
    .name:           _Z11mega_kernel6Params
    .private_segment_fixed_size: 0
    .sgpr_count:     108
    .sgpr_spill_count: 134
    .symbol:         _Z11mega_kernel6Params.kd
    .uniform_work_group_size: 1
    .uses_dynamic_stack: false
    .vgpr_count:     256
    .vgpr_spill_count: 0
    .wavefront_size: 64
